# GEMM K-loops: per-accumulator k-steps back-to-back, n-major snake order, end-of-segment barrier moved up 4 MFMAs
# speedup vs baseline: 1.0146x; 1.0039x over previous
; #define PG8_STAGE(bufoff, gbase, voff) do { _Pragma("unroll") for (int _i = 0; _i < 2; ++_i) \
;         __builtin_amdgcn_global_load_lds((const unsigned*)((const char*)(gbase) + (voff)[_i]), (PG8_LAS unsigned*)(lds + (bufoff) + ldsw + _i * 8192), 16, 0, 0); } while (0)
; #define PG8_LDA(dst, b, h) do { _Pragma("unroll") for (int m = 0; m < 4; ++m) _Pragma("unroll") for (int k = 0; k < 2; ++k) dst[m][k] = *(const PG8_LAS bf16x8*)(lds + PG8_SA(b, h) + aoff + m * 2048 + k * 1024); } while (0)
; #define PG8_LDB(dst, b, h) do { _Pragma("unroll") for (int n = 0; n < 2; ++n) _Pragma("unroll") for (int k = 0; k < 2; ++k) dst[n][k] = *(const PG8_LAS bf16x8*)(lds + PG8_SB(b, h) + boff + n * 2048 + k * 1024); } while (0)
; #define PG8_MMA(ai, bj, At, Bt) do { __builtin_amdgcn_s_setprio(1); _Pragma("unroll") for (int m = 0; m < 4; ++m) _Pragma("unroll") for (int n = 0; n < 2; ++n) _Pragma("unroll") for (int k = 0; k < 2; ++k) \
;         acc[ai][bj][m][n] = __builtin_amdgcn_mfma_f32_16x16x32_bf16(Bt[n][k], At[m][k], acc[ai][bj][m][n], 0, 0, 0); __builtin_amdgcn_s_setprio(0); } while (0)
; #define PG8_WAIT_V(n) asm volatile("s_waitcnt vmcnt(" #n ")" ::: "memory")
; #define PG8_WAIT_L(n) asm volatile("s_waitcnt lgkmcnt(" #n ")" ::: "memory")
; #define PG8_BAR __builtin_amdgcn_s_barrier()
; #define PG8_SCHED __builtin_amdgcn_sched_barrier(0)
; template <class Epi, class Sched, bool ALIGN_EPI = false, bool SP2 = false>
; __device__ __forceinline__ void gemm_phase(PG8_LAS unsigned char* lds, const Gemm g, const Sched& S, const Epi& E) {
;     ...
;             PG8_LDB(B0, 0, 0); PG8_LDB(B1, 0, 1); PG8_SCHED; PG8_LDA(At, 0, 0); PG8_STAGE(PG8_SA(1, 1), a1 + hstep, voffA);
;             PG8_WAIT_V(8); PG8_WAIT_L(0); PG8_BAR; PG8_MMA(0, 0, At, B0); PG8_MMA(0, 1, At, B1); PG8_BAR; PG8_SCHED;
;             PG8_LDA(At, 0, 1); PG8_STAGE(PG8_SB(0, 0), b2, voffB); PG8_STAGE(PG8_SB(0, 1), b2 + hstep, voffB); PG8_STAGE(PG8_SA(0, 0), a2, voffA);
;             PG8_WAIT_V(8); PG8_WAIT_L(0); PG8_BAR; PG8_MMA(1, 0, At, B0); PG8_MMA(1, 1, At, B1); PG8_BAR; PG8_SCHED;
.LBB0_102:
	ds_read_b128 v[160:163], v155
	ds_read_b128 v[164:167], v155 offset:1024
	ds_read_b128 v[168:171], v155 offset:2048
	ds_read_b128 v[172:175], v155 offset:3072
	ds_read_b128 v[176:179], v157
	ds_read_b128 v[180:183], v157 offset:1024
	ds_read_b128 v[184:187], v157 offset:2048
	ds_read_b128 v[188:191], v157 offset:3072
	s_add_u32 s62, s74, 0xfff80080
	s_addc_u32 s63, s75, -1
	s_cmp_eq_u32 s90, 28
	s_cselect_b32 s79, s10, s63
	s_cselect_b32 s78, s11, s62
	s_cselect_b32 s77, s51, s89
	s_cselect_b32 s76, s55, s88
	v_lshl_add_u64 v[224:225], s[74:75], 0, v[138:139]
	s_add_i32 m0, s61, 0xc000
	ds_read_b128 v[192:195], v159
	ds_read_b128 v[196:199], v159 offset:1024
	ds_read_b128 v[200:203], v159 offset:2048
	ds_read_b128 v[204:207], v159 offset:3072
	ds_read_b128 v[208:211], v159 offset:4096
	ds_read_b128 v[212:215], v159 offset:5120
	ds_read_b128 v[216:219], v159 offset:6144
	ds_read_b128 v[220:223], v159 offset:7168
	global_load_lds_dwordx4 v[224:225], off
	v_lshl_add_u64 v[224:225], s[74:75], 0, v[140:141]
	s_add_i32 m0, s61, 0xe000
	s_nop 0
	global_load_lds_dwordx4 v[224:225], off
	s_waitcnt vmcnt(8)
	s_waitcnt lgkmcnt(0)
	s_setprio 1
	s_barrier
	v_mfma_f32_16x16x32_bf16 v[124:127], v[160:163], v[192:195], v[124:127]
	v_mfma_f32_16x16x32_bf16 v[124:127], v[164:167], v[196:199], v[124:127]
	v_mfma_f32_16x16x32_bf16 v[108:111], v[160:163], v[200:203], v[108:111]
	v_mfma_f32_16x16x32_bf16 v[108:111], v[164:167], v[204:207], v[108:111]
	v_mfma_f32_16x16x32_bf16 v[92:95], v[160:163], v[208:211], v[92:95]
	v_mfma_f32_16x16x32_bf16 v[92:95], v[164:167], v[212:215], v[92:95]
	v_mfma_f32_16x16x32_bf16 v[76:79], v[160:163], v[216:219], v[76:79]
	v_mfma_f32_16x16x32_bf16 v[76:79], v[164:167], v[220:223], v[76:79]
	v_mfma_f32_16x16x32_bf16 v[72:75], v[168:171], v[216:219], v[72:75]
	v_mfma_f32_16x16x32_bf16 v[72:75], v[172:175], v[220:223], v[72:75]
	v_mfma_f32_16x16x32_bf16 v[88:91], v[168:171], v[208:211], v[88:91]
	v_mfma_f32_16x16x32_bf16 v[88:91], v[172:175], v[212:215], v[88:91]
	v_mfma_f32_16x16x32_bf16 v[104:107], v[168:171], v[200:203], v[104:107]
	v_mfma_f32_16x16x32_bf16 v[104:107], v[172:175], v[204:207], v[104:107]
	v_mfma_f32_16x16x32_bf16 v[120:123], v[168:171], v[192:195], v[120:123]
	v_mfma_f32_16x16x32_bf16 v[120:123], v[172:175], v[196:199], v[120:123]
	v_mfma_f32_16x16x32_bf16 v[116:119], v[176:179], v[192:195], v[116:119]
	v_mfma_f32_16x16x32_bf16 v[116:119], v[180:183], v[196:199], v[116:119]
	v_mfma_f32_16x16x32_bf16 v[100:103], v[176:179], v[200:203], v[100:103]
	v_mfma_f32_16x16x32_bf16 v[100:103], v[180:183], v[204:207], v[100:103]
	v_mfma_f32_16x16x32_bf16 v[84:87], v[176:179], v[208:211], v[84:87]
	v_mfma_f32_16x16x32_bf16 v[84:87], v[180:183], v[212:215], v[84:87]
	v_mfma_f32_16x16x32_bf16 v[68:71], v[176:179], v[216:219], v[68:71]
	v_mfma_f32_16x16x32_bf16 v[68:71], v[180:183], v[220:223], v[68:71]
	v_mfma_f32_16x16x32_bf16 v[64:67], v[184:187], v[216:219], v[64:67]
	v_mfma_f32_16x16x32_bf16 v[64:67], v[188:191], v[220:223], v[64:67]
	v_mfma_f32_16x16x32_bf16 v[80:83], v[184:187], v[208:211], v[80:83]
	v_mfma_f32_16x16x32_bf16 v[80:83], v[188:191], v[212:215], v[80:83]
	s_setprio 2
	s_barrier
	v_mfma_f32_16x16x32_bf16 v[96:99], v[184:187], v[200:203], v[96:99]
	v_mfma_f32_16x16x32_bf16 v[96:99], v[188:191], v[204:207], v[96:99]
	v_mfma_f32_16x16x32_bf16 v[112:115], v[184:187], v[192:195], v[112:115]
	v_mfma_f32_16x16x32_bf16 v[112:115], v[188:191], v[196:199], v[112:115]
	s_setprio 0
	s_add_i32 s62, s84, s35
	v_lshl_add_u64 v[224:225], s[76:77], 0, v[130:131]
	s_mov_b32 m0, s62
	ds_read_b128 v[192:195], v159 offset:16384
	ds_read_b128 v[196:199], v159 offset:17408
	ds_read_b128 v[200:203], v159 offset:18432
	ds_read_b128 v[204:207], v159 offset:19456
	ds_read_b128 v[208:211], v159 offset:20480
	ds_read_b128 v[212:215], v159 offset:21504
	ds_read_b128 v[216:219], v159 offset:22528
	ds_read_b128 v[220:223], v159 offset:23552
	global_load_lds_dwordx4 v[224:225], off
	s_add_i32 m0, s62, 0x2000
	s_add_u32 s92, s76, 0x80000
	v_lshl_add_u64 v[226:227], s[76:77], 0, v[134:135]
	s_addc_u32 s93, s77, 0
	s_add_i32 s62, s85, s35
	global_load_lds_dwordx4 v[226:227], off
	v_lshl_add_u64 v[228:229], s[92:93], 0, v[130:131]
	s_mov_b32 m0, s62
	v_lshl_add_u64 v[230:231], s[78:79], 0, v[132:133]
	global_load_lds_dwordx4 v[228:229], off
	v_lshl_add_u64 v[228:229], s[92:93], 0, v[134:135]
	s_add_i32 m0, s62, 0x2000
	s_nop 0
	global_load_lds_dwordx4 v[228:229], off
	v_lshl_add_u64 v[228:229], s[78:79], 0, v[128:129]
	s_mov_b32 m0, s61
	s_nop 0
	global_load_lds_dwordx4 v[228:229], off
	s_mov_b32 m0, s65
	s_nop 0
	global_load_lds_dwordx4 v[230:231], off
	s_waitcnt vmcnt(8)
	s_waitcnt lgkmcnt(0)
	s_setprio 1
	s_barrier
; #define PG8_STAGE(bufoff, gbase, voff) do { _Pragma("unroll") for (int _i = 0; _i < 2; ++_i) \
;         __builtin_amdgcn_global_load_lds((const unsigned*)((const char*)(gbase) + (voff)[_i]), (PG8_LAS unsigned*)(lds + (bufoff) + ldsw + _i * 8192), 16, 0, 0); } while (0)
; #define PG8_LDA(dst, b, h) do { _Pragma("unroll") for (int m = 0; m < 4; ++m) _Pragma("unroll") for (int k = 0; k < 2; ++k) dst[m][k] = *(const PG8_LAS bf16x8*)(lds + PG8_SA(b, h) + aoff + m * 2048 + k * 1024); } while (0)
; #define PG8_LDB(dst, b, h) do { _Pragma("unroll") for (int n = 0; n < 2; ++n) _Pragma("unroll") for (int k = 0; k < 2; ++k) dst[n][k] = *(const PG8_LAS bf16x8*)(lds + PG8_SB(b, h) + boff + n * 2048 + k * 1024); } while (0)
; #define PG8_MMA(ai, bj, At, Bt) do { __builtin_amdgcn_s_setprio(1); _Pragma("unroll") for (int m = 0; m < 4; ++m) _Pragma("unroll") for (int n = 0; n < 2; ++n) _Pragma("unroll") for (int k = 0; k < 2; ++k) \
;         acc[ai][bj][m][n] = __builtin_amdgcn_mfma_f32_16x16x32_bf16(Bt[n][k], At[m][k], acc[ai][bj][m][n], 0, 0, 0); __builtin_amdgcn_s_setprio(0); } while (0)
; #define PG8_WAIT_V(n) asm volatile("s_waitcnt vmcnt(" #n ")" ::: "memory")
; #define PG8_WAIT_L(n) asm volatile("s_waitcnt lgkmcnt(" #n ")" ::: "memory")
; #define PG8_BAR __builtin_amdgcn_s_barrier()
; #define PG8_SCHED __builtin_amdgcn_sched_barrier(0)
; template <class Epi, class Sched, bool ALIGN_EPI = false, bool SP2 = false>
; __device__ __forceinline__ void gemm_phase(PG8_LAS unsigned char* lds, const Gemm g, const Sched& S, const Epi& E) {
;     ...
;             PG8_WAIT_V(8); PG8_WAIT_L(0); PG8_BAR; PG8_MMA(1, 0, At, B0); PG8_MMA(1, 1, At, B1); PG8_BAR; PG8_SCHED;
;             PG8_LDB(B0, 1, 0); PG8_LDB(B1, 1, 1); PG8_SCHED; PG8_LDA(At, 1, 0); PG8_STAGE(PG8_SA(0, 1), a2 + hstep, voffA);
;             PG8_WAIT_V(8); PG8_WAIT_L(0); PG8_BAR; PG8_MMA(0, 0, At, B0); PG8_MMA(0, 1, At, B1); PG8_BAR; PG8_SCHED;
	v_mfma_f32_16x16x32_bf16 v[60:63], v[160:163], v[192:195], v[60:63]
	v_mfma_f32_16x16x32_bf16 v[60:63], v[164:167], v[196:199], v[60:63]
	v_mfma_f32_16x16x32_bf16 v[44:47], v[160:163], v[200:203], v[44:47]
	v_mfma_f32_16x16x32_bf16 v[44:47], v[164:167], v[204:207], v[44:47]
	v_mfma_f32_16x16x32_bf16 v[28:31], v[160:163], v[208:211], v[28:31]
	v_mfma_f32_16x16x32_bf16 v[28:31], v[164:167], v[212:215], v[28:31]
	v_mfma_f32_16x16x32_bf16 v[12:15], v[160:163], v[216:219], v[12:15]
	v_mfma_f32_16x16x32_bf16 v[12:15], v[164:167], v[220:223], v[12:15]
	v_mfma_f32_16x16x32_bf16 v[8:11], v[168:171], v[216:219], v[8:11]
	v_mfma_f32_16x16x32_bf16 v[8:11], v[172:175], v[220:223], v[8:11]
	v_mfma_f32_16x16x32_bf16 v[24:27], v[168:171], v[208:211], v[24:27]
	v_mfma_f32_16x16x32_bf16 v[24:27], v[172:175], v[212:215], v[24:27]
	v_mfma_f32_16x16x32_bf16 v[40:43], v[168:171], v[200:203], v[40:43]
	v_mfma_f32_16x16x32_bf16 v[40:43], v[172:175], v[204:207], v[40:43]
	v_mfma_f32_16x16x32_bf16 v[56:59], v[168:171], v[192:195], v[56:59]
	v_mfma_f32_16x16x32_bf16 v[56:59], v[172:175], v[196:199], v[56:59]
	v_mfma_f32_16x16x32_bf16 v[52:55], v[176:179], v[192:195], v[52:55]
	v_mfma_f32_16x16x32_bf16 v[52:55], v[180:183], v[196:199], v[52:55]
	v_mfma_f32_16x16x32_bf16 v[36:39], v[176:179], v[200:203], v[36:39]
	v_mfma_f32_16x16x32_bf16 v[36:39], v[180:183], v[204:207], v[36:39]
	v_mfma_f32_16x16x32_bf16 v[20:23], v[176:179], v[208:211], v[20:23]
	v_mfma_f32_16x16x32_bf16 v[20:23], v[180:183], v[212:215], v[20:23]
	v_mfma_f32_16x16x32_bf16 v[4:7], v[176:179], v[216:219], v[4:7]
	v_mfma_f32_16x16x32_bf16 v[4:7], v[180:183], v[220:223], v[4:7]
	v_mfma_f32_16x16x32_bf16 v[0:3], v[184:187], v[216:219], v[0:3]
	v_mfma_f32_16x16x32_bf16 v[0:3], v[188:191], v[220:223], v[0:3]
	v_mfma_f32_16x16x32_bf16 v[16:19], v[184:187], v[208:211], v[16:19]
	v_mfma_f32_16x16x32_bf16 v[16:19], v[188:191], v[212:215], v[16:19]
	s_setprio 2
	s_barrier
	v_mfma_f32_16x16x32_bf16 v[32:35], v[184:187], v[200:203], v[32:35]
	v_mfma_f32_16x16x32_bf16 v[32:35], v[188:191], v[204:207], v[32:35]
	v_mfma_f32_16x16x32_bf16 v[48:51], v[184:187], v[192:195], v[48:51]
	v_mfma_f32_16x16x32_bf16 v[48:51], v[188:191], v[196:199], v[48:51]
	s_setprio 0
	s_add_i32 s62, 0, 0x18000
	s_add_i32 s63, 0, 0x1c000
	v_add_u32_e32 v172, s62, v147
	v_add_u32_e32 v188, s63, v147
	ds_read_b128 v[160:163], v172
	ds_read_b128 v[164:167], v172 offset:1024
	ds_read_b128 v[168:171], v172 offset:2048
	ds_read_b128 v[172:175], v172 offset:3072
	ds_read_b128 v[176:179], v188
	ds_read_b128 v[180:183], v188 offset:1024
	ds_read_b128 v[184:187], v188 offset:2048
	ds_read_b128 v[188:191], v188 offset:3072
	s_add_u32 s78, s78, 0x80000
	s_addc_u32 s79, s79, 0
	s_mov_b32 m0, s66
	v_lshl_add_u64 v[232:233], s[78:79], 0, v[128:129]
	ds_read_b128 v[192:195], v159 offset:32768
	ds_read_b128 v[196:199], v159 offset:33792
	ds_read_b128 v[200:203], v159 offset:34816
	ds_read_b128 v[204:207], v159 offset:35840
	ds_read_b128 v[208:211], v159 offset:36864
	ds_read_b128 v[212:215], v159 offset:37888
	ds_read_b128 v[216:219], v159 offset:38912
	ds_read_b128 v[220:223], v159 offset:39936
	global_load_lds_dwordx4 v[232:233], off
	v_lshl_add_u64 v[232:233], s[78:79], 0, v[132:133]
	s_mov_b32 m0, s67
	s_nop 0
	global_load_lds_dwordx4 v[232:233], off
	s_waitcnt vmcnt(8)
	s_waitcnt lgkmcnt(0)
	s_setprio 1
	s_barrier
	v_mfma_f32_16x16x32_bf16 v[124:127], v[160:163], v[192:195], v[124:127]
	v_mfma_f32_16x16x32_bf16 v[124:127], v[164:167], v[196:199], v[124:127]
	v_mfma_f32_16x16x32_bf16 v[108:111], v[160:163], v[200:203], v[108:111]
	v_mfma_f32_16x16x32_bf16 v[108:111], v[164:167], v[204:207], v[108:111]
	v_mfma_f32_16x16x32_bf16 v[92:95], v[160:163], v[208:211], v[92:95]
	v_mfma_f32_16x16x32_bf16 v[92:95], v[164:167], v[212:215], v[92:95]
	v_mfma_f32_16x16x32_bf16 v[76:79], v[160:163], v[216:219], v[76:79]
	v_mfma_f32_16x16x32_bf16 v[76:79], v[164:167], v[220:223], v[76:79]
	v_mfma_f32_16x16x32_bf16 v[72:75], v[168:171], v[216:219], v[72:75]
	v_mfma_f32_16x16x32_bf16 v[72:75], v[172:175], v[220:223], v[72:75]
	v_mfma_f32_16x16x32_bf16 v[88:91], v[168:171], v[208:211], v[88:91]
	v_mfma_f32_16x16x32_bf16 v[88:91], v[172:175], v[212:215], v[88:91]
	v_mfma_f32_16x16x32_bf16 v[104:107], v[168:171], v[200:203], v[104:107]
	v_mfma_f32_16x16x32_bf16 v[104:107], v[172:175], v[204:207], v[104:107]
	v_mfma_f32_16x16x32_bf16 v[120:123], v[168:171], v[192:195], v[120:123]
	v_mfma_f32_16x16x32_bf16 v[120:123], v[172:175], v[196:199], v[120:123]
	v_mfma_f32_16x16x32_bf16 v[116:119], v[176:179], v[192:195], v[116:119]
	v_mfma_f32_16x16x32_bf16 v[116:119], v[180:183], v[196:199], v[116:119]
	v_mfma_f32_16x16x32_bf16 v[100:103], v[176:179], v[200:203], v[100:103]
	v_mfma_f32_16x16x32_bf16 v[100:103], v[180:183], v[204:207], v[100:103]
	v_mfma_f32_16x16x32_bf16 v[84:87], v[176:179], v[208:211], v[84:87]
	v_mfma_f32_16x16x32_bf16 v[84:87], v[180:183], v[212:215], v[84:87]
	v_mfma_f32_16x16x32_bf16 v[68:71], v[176:179], v[216:219], v[68:71]
	v_mfma_f32_16x16x32_bf16 v[68:71], v[180:183], v[220:223], v[68:71]
	v_mfma_f32_16x16x32_bf16 v[64:67], v[184:187], v[216:219], v[64:67]
	v_mfma_f32_16x16x32_bf16 v[64:67], v[188:191], v[220:223], v[64:67]
	v_mfma_f32_16x16x32_bf16 v[80:83], v[184:187], v[208:211], v[80:83]
	v_mfma_f32_16x16x32_bf16 v[80:83], v[188:191], v[212:215], v[80:83]
	s_setprio 2
	s_barrier
; #define PG8_STAGE(bufoff, gbase, voff) do { _Pragma("unroll") for (int _i = 0; _i < 2; ++_i) \
;         __builtin_amdgcn_global_load_lds((const unsigned*)((const char*)(gbase) + (voff)[_i]), (PG8_LAS unsigned*)(lds + (bufoff) + ldsw + _i * 8192), 16, 0, 0); } while (0)
; #define PG8_LDA(dst, b, h) do { _Pragma("unroll") for (int m = 0; m < 4; ++m) _Pragma("unroll") for (int k = 0; k < 2; ++k) dst[m][k] = *(const PG8_LAS bf16x8*)(lds + PG8_SA(b, h) + aoff + m * 2048 + k * 1024); } while (0)
; #define PG8_MMA(ai, bj, At, Bt) do { __builtin_amdgcn_s_setprio(1); _Pragma("unroll") for (int m = 0; m < 4; ++m) _Pragma("unroll") for (int n = 0; n < 2; ++n) _Pragma("unroll") for (int k = 0; k < 2; ++k) \
;         acc[ai][bj][m][n] = __builtin_amdgcn_mfma_f32_16x16x32_bf16(Bt[n][k], At[m][k], acc[ai][bj][m][n], 0, 0, 0); __builtin_amdgcn_s_setprio(0); } while (0)
; #define PG8_WAIT_V(n) asm volatile("s_waitcnt vmcnt(" #n ")" ::: "memory")
; #define PG8_WAIT_L(n) asm volatile("s_waitcnt lgkmcnt(" #n ")" ::: "memory")
; #define PG8_BAR __builtin_amdgcn_s_barrier()
; #define PG8_SCHED __builtin_amdgcn_sched_barrier(0)
; template <class Epi, class Sched, bool ALIGN_EPI = false, bool SP2 = false>
; __device__ __forceinline__ void gemm_phase(PG8_LAS unsigned char* lds, const Gemm g, const Sched& S, const Epi& E) {
;     ...
;             PG8_LDA(At, 1, 1); PG8_STAGE(PG8_SB(1, 0), b3, voffB); PG8_STAGE(PG8_SB(1, 1), b3 + hstep, voffB); PG8_STAGE(PG8_SA(1, 0), a3, voffA);
;             PG8_WAIT_V(8); PG8_WAIT_L(0); PG8_BAR; PG8_MMA(1, 0, At, B0); PG8_MMA(1, 1, At, B1); PG8_BAR; PG8_SCHED;
;     ...
;         if constexpr (ALIGN_EPI) { if (wr == 0) PG8_BAR; }
	v_mfma_f32_16x16x32_bf16 v[96:99], v[184:187], v[200:203], v[96:99]
	v_mfma_f32_16x16x32_bf16 v[96:99], v[188:191], v[204:207], v[96:99]
	v_mfma_f32_16x16x32_bf16 v[112:115], v[184:187], v[192:195], v[112:115]
	v_mfma_f32_16x16x32_bf16 v[112:115], v[188:191], v[196:199], v[112:115]
	s_setprio 0
	s_add_i32 s62, s62, s35
	v_lshl_add_u64 v[224:225], v[224:225], 0, s[18:19]
	s_mov_b32 m0, s62
	ds_read_b128 v[192:195], v159 offset:49152
	ds_read_b128 v[196:199], v159 offset:50176
	ds_read_b128 v[200:203], v159 offset:51200
	ds_read_b128 v[204:207], v159 offset:52224
	ds_read_b128 v[208:211], v159 offset:53248
	ds_read_b128 v[212:215], v159 offset:54272
	ds_read_b128 v[216:219], v159 offset:55296
	ds_read_b128 v[220:223], v159 offset:56320
	global_load_lds_dwordx4 v[224:225], off
	s_add_i32 m0, s62, 0x2000
	s_add_u32 s76, s76, 0x80080
	v_lshl_add_u64 v[224:225], v[226:227], 0, s[18:19]
	s_addc_u32 s77, s77, 0
	s_add_i32 s62, s63, s35
	global_load_lds_dwordx4 v[224:225], off
	v_lshl_add_u64 v[224:225], s[76:77], 0, v[130:131]
	s_mov_b32 m0, s62
	s_nop 0
	global_load_lds_dwordx4 v[224:225], off
	v_lshl_add_u64 v[224:225], s[76:77], 0, v[134:135]
	s_add_i32 m0, s62, 0x2000
	s_nop 0
	global_load_lds_dwordx4 v[224:225], off
	v_lshl_add_u64 v[224:225], v[228:229], 0, s[18:19]
	s_mov_b32 m0, s81
	s_nop 0
	global_load_lds_dwordx4 v[224:225], off
	v_lshl_add_u64 v[224:225], v[230:231], 0, s[18:19]
	s_mov_b32 m0, s82
	s_nop 0
	global_load_lds_dwordx4 v[224:225], off
	s_waitcnt vmcnt(8)
	s_waitcnt lgkmcnt(0)
	s_setprio 1
	s_barrier
	v_mfma_f32_16x16x32_bf16 v[60:63], v[160:163], v[192:195], v[60:63]
	v_mfma_f32_16x16x32_bf16 v[60:63], v[164:167], v[196:199], v[60:63]
	v_mfma_f32_16x16x32_bf16 v[44:47], v[160:163], v[200:203], v[44:47]
	v_mfma_f32_16x16x32_bf16 v[44:47], v[164:167], v[204:207], v[44:47]
	v_mfma_f32_16x16x32_bf16 v[28:31], v[160:163], v[208:211], v[28:31]
	v_mfma_f32_16x16x32_bf16 v[28:31], v[164:167], v[212:215], v[28:31]
	v_mfma_f32_16x16x32_bf16 v[12:15], v[160:163], v[216:219], v[12:15]
	v_mfma_f32_16x16x32_bf16 v[12:15], v[164:167], v[220:223], v[12:15]
	v_mfma_f32_16x16x32_bf16 v[8:11], v[168:171], v[216:219], v[8:11]
	v_mfma_f32_16x16x32_bf16 v[8:11], v[172:175], v[220:223], v[8:11]
	v_mfma_f32_16x16x32_bf16 v[24:27], v[168:171], v[208:211], v[24:27]
	v_mfma_f32_16x16x32_bf16 v[24:27], v[172:175], v[212:215], v[24:27]
	v_mfma_f32_16x16x32_bf16 v[40:43], v[168:171], v[200:203], v[40:43]
	v_mfma_f32_16x16x32_bf16 v[40:43], v[172:175], v[204:207], v[40:43]
	v_mfma_f32_16x16x32_bf16 v[56:59], v[168:171], v[192:195], v[56:59]
	v_mfma_f32_16x16x32_bf16 v[56:59], v[172:175], v[196:199], v[56:59]
	v_mfma_f32_16x16x32_bf16 v[52:55], v[176:179], v[192:195], v[52:55]
	v_mfma_f32_16x16x32_bf16 v[52:55], v[180:183], v[196:199], v[52:55]
	v_mfma_f32_16x16x32_bf16 v[36:39], v[176:179], v[200:203], v[36:39]
	v_mfma_f32_16x16x32_bf16 v[36:39], v[180:183], v[204:207], v[36:39]
	v_mfma_f32_16x16x32_bf16 v[20:23], v[176:179], v[208:211], v[20:23]
	v_mfma_f32_16x16x32_bf16 v[20:23], v[180:183], v[212:215], v[20:23]
	v_mfma_f32_16x16x32_bf16 v[4:7], v[176:179], v[216:219], v[4:7]
	v_mfma_f32_16x16x32_bf16 v[4:7], v[180:183], v[220:223], v[4:7]
	v_mfma_f32_16x16x32_bf16 v[0:3], v[184:187], v[216:219], v[0:3]
	v_mfma_f32_16x16x32_bf16 v[0:3], v[188:191], v[220:223], v[0:3]
	v_mfma_f32_16x16x32_bf16 v[16:19], v[184:187], v[208:211], v[16:19]
	v_mfma_f32_16x16x32_bf16 v[16:19], v[188:191], v[212:215], v[16:19]
	s_setprio 2
	s_barrier
	v_mfma_f32_16x16x32_bf16 v[32:35], v[184:187], v[200:203], v[32:35]
	v_mfma_f32_16x16x32_bf16 v[32:35], v[188:191], v[204:207], v[32:35]
	v_mfma_f32_16x16x32_bf16 v[48:51], v[184:187], v[192:195], v[48:51]
	v_mfma_f32_16x16x32_bf16 v[48:51], v[188:191], v[196:199], v[48:51]
	s_setprio 0
	s_add_i32 s90, s90, 2
	s_add_u32 s74, s74, 0x100
	s_addc_u32 s75, s75, 0
	s_add_u32 s88, s88, 0x100
	s_addc_u32 s89, s89, 0
	s_cmp_gt_u32 s90, 29
	s_cbranch_scc0 .LBB0_102
	s_and_b64 vcc, exec, s[22:23]
	s_cbranch_vccz .LBB0_105
	s_barrier

; #define PG8_STAGE(bufoff, gbase, voff) do { _Pragma("unroll") for (int _i = 0; _i < 2; ++_i) \
;         __builtin_amdgcn_global_load_lds((const unsigned*)((const char*)(gbase) + (voff)[_i]), (PG8_LAS unsigned*)(lds + (bufoff) + ldsw + _i * 8192), 16, 0, 0); } while (0)
; #define PG8_LDA(dst, b, h) do { _Pragma("unroll") for (int m = 0; m < 4; ++m) _Pragma("unroll") for (int k = 0; k < 2; ++k) dst[m][k] = *(const PG8_LAS bf16x8*)(lds + PG8_SA(b, h) + aoff + m * 2048 + k * 1024); } while (0)
; #define PG8_LDB(dst, b, h) do { _Pragma("unroll") for (int n = 0; n < 2; ++n) _Pragma("unroll") for (int k = 0; k < 2; ++k) dst[n][k] = *(const PG8_LAS bf16x8*)(lds + PG8_SB(b, h) + boff + n * 2048 + k * 1024); } while (0)
; #define PG8_MMA(ai, bj, At, Bt) do { __builtin_amdgcn_s_setprio(1); _Pragma("unroll") for (int m = 0; m < 4; ++m) _Pragma("unroll") for (int n = 0; n < 2; ++n) _Pragma("unroll") for (int k = 0; k < 2; ++k) \
;         acc[ai][bj][m][n] = __builtin_amdgcn_mfma_f32_16x16x32_bf16(Bt[n][k], At[m][k], acc[ai][bj][m][n], 0, 0, 0); __builtin_amdgcn_s_setprio(0); } while (0)
; #define PG8_WAIT_V(n) asm volatile("s_waitcnt vmcnt(" #n ")" ::: "memory")
; #define PG8_WAIT_L(n) asm volatile("s_waitcnt lgkmcnt(" #n ")" ::: "memory")
; #define PG8_BAR __builtin_amdgcn_s_barrier()
; #define PG8_SCHED __builtin_amdgcn_sched_barrier(0)
; template <class Epi, class Sched, bool ALIGN_EPI = false, bool SP2 = false>
; __device__ __forceinline__ void gemm_phase(PG8_LAS unsigned char* lds, const Gemm g, const Sched& S, const Epi& E) {
;     ...
;             PG8_LDB(B0, 0, 0); PG8_LDB(B1, 0, 1); PG8_SCHED; PG8_LDA(At, 0, 0); PG8_STAGE(PG8_SA(1, 1), a1 + hstep, voffA);
;             PG8_WAIT_V(8); PG8_WAIT_L(0); PG8_BAR; PG8_MMA(0, 0, At, B0); PG8_MMA(0, 1, At, B1); PG8_BAR; PG8_SCHED;
;             PG8_LDA(At, 0, 1); PG8_STAGE(PG8_SB(0, 0), b2, voffB); PG8_STAGE(PG8_SB(0, 1), b2 + hstep, voffB); PG8_STAGE(PG8_SA(0, 0), a2, voffA);
;             PG8_WAIT_V(8); PG8_WAIT_L(0); PG8_BAR; PG8_MMA(1, 0, At, B0); PG8_MMA(1, 1, At, B1); PG8_BAR; PG8_SCHED;
.LBB0_179:
	ds_read_b128 v[144:147], v155
	ds_read_b128 v[160:163], v155 offset:1024
	ds_read_b128 v[164:167], v155 offset:2048
	ds_read_b128 v[168:171], v155 offset:3072
	ds_read_b128 v[172:175], v156
	ds_read_b128 v[176:179], v156 offset:1024
	ds_read_b128 v[180:183], v156 offset:2048
	ds_read_b128 v[184:187], v156 offset:3072
	s_add_u32 s62, s76, 0xffea0080
	s_addc_u32 s63, s77, -1
	s_cmpk_eq_i32 s92, 0x54
	s_cselect_b32 s81, s7, s63
	s_cselect_b32 s80, s6, s62
	s_cselect_b32 s79, s75, s91
	s_cselect_b32 s78, s74, s50
	v_lshl_add_u64 v[220:221], s[76:77], 0, v[136:137]
	s_add_i32 m0, s52, 0xc000
	ds_read_b128 v[188:191], v157
	ds_read_b128 v[192:195], v157 offset:1024
	ds_read_b128 v[196:199], v157 offset:2048
	ds_read_b128 v[200:203], v157 offset:3072
	ds_read_b128 v[204:207], v157 offset:4096
	ds_read_b128 v[208:211], v157 offset:5120
	ds_read_b128 v[212:215], v157 offset:6144
	ds_read_b128 v[216:219], v157 offset:7168
	global_load_lds_dwordx4 v[220:221], off
	v_lshl_add_u64 v[220:221], s[76:77], 0, v[138:139]
	s_add_i32 m0, s52, 0xe000
	s_nop 0
	global_load_lds_dwordx4 v[220:221], off
	s_waitcnt vmcnt(8)
	s_waitcnt lgkmcnt(0)
	s_setprio 1
	s_barrier
	v_mfma_f32_16x16x32_bf16 v[124:127], v[144:147], v[188:191], v[124:127]
	v_mfma_f32_16x16x32_bf16 v[124:127], v[160:163], v[192:195], v[124:127]
	v_mfma_f32_16x16x32_bf16 v[108:111], v[144:147], v[196:199], v[108:111]
	v_mfma_f32_16x16x32_bf16 v[108:111], v[160:163], v[200:203], v[108:111]
	v_mfma_f32_16x16x32_bf16 v[92:95], v[144:147], v[204:207], v[92:95]
	v_mfma_f32_16x16x32_bf16 v[92:95], v[160:163], v[208:211], v[92:95]
	v_mfma_f32_16x16x32_bf16 v[76:79], v[144:147], v[212:215], v[76:79]
	v_mfma_f32_16x16x32_bf16 v[76:79], v[160:163], v[216:219], v[76:79]
	v_mfma_f32_16x16x32_bf16 v[72:75], v[164:167], v[212:215], v[72:75]
	v_mfma_f32_16x16x32_bf16 v[72:75], v[168:171], v[216:219], v[72:75]
	v_mfma_f32_16x16x32_bf16 v[88:91], v[164:167], v[204:207], v[88:91]
	v_mfma_f32_16x16x32_bf16 v[88:91], v[168:171], v[208:211], v[88:91]
	v_mfma_f32_16x16x32_bf16 v[104:107], v[164:167], v[196:199], v[104:107]
	v_mfma_f32_16x16x32_bf16 v[104:107], v[168:171], v[200:203], v[104:107]
	v_mfma_f32_16x16x32_bf16 v[120:123], v[164:167], v[188:191], v[120:123]
	v_mfma_f32_16x16x32_bf16 v[120:123], v[168:171], v[192:195], v[120:123]
	v_mfma_f32_16x16x32_bf16 v[116:119], v[172:175], v[188:191], v[116:119]
	v_mfma_f32_16x16x32_bf16 v[116:119], v[176:179], v[192:195], v[116:119]
	v_mfma_f32_16x16x32_bf16 v[100:103], v[172:175], v[196:199], v[100:103]
	v_mfma_f32_16x16x32_bf16 v[100:103], v[176:179], v[200:203], v[100:103]
	v_mfma_f32_16x16x32_bf16 v[84:87], v[172:175], v[204:207], v[84:87]
	v_mfma_f32_16x16x32_bf16 v[84:87], v[176:179], v[208:211], v[84:87]
	v_mfma_f32_16x16x32_bf16 v[68:71], v[172:175], v[212:215], v[68:71]
	v_mfma_f32_16x16x32_bf16 v[68:71], v[176:179], v[216:219], v[68:71]
	v_mfma_f32_16x16x32_bf16 v[64:67], v[180:183], v[212:215], v[64:67]
	v_mfma_f32_16x16x32_bf16 v[64:67], v[184:187], v[216:219], v[64:67]
	v_mfma_f32_16x16x32_bf16 v[80:83], v[180:183], v[204:207], v[80:83]
	v_mfma_f32_16x16x32_bf16 v[80:83], v[184:187], v[208:211], v[80:83]
	s_setprio 2
	s_barrier
	v_mfma_f32_16x16x32_bf16 v[96:99], v[180:183], v[196:199], v[96:99]
	v_mfma_f32_16x16x32_bf16 v[96:99], v[184:187], v[200:203], v[96:99]
	v_mfma_f32_16x16x32_bf16 v[112:115], v[180:183], v[188:191], v[112:115]
	v_mfma_f32_16x16x32_bf16 v[112:115], v[184:187], v[192:195], v[112:115]
	s_setprio 0
	s_add_i32 s62, s86, s35
	v_lshl_add_u64 v[220:221], s[78:79], 0, v[130:131]
	s_mov_b32 m0, s62
	ds_read_b128 v[188:191], v157 offset:16384
	ds_read_b128 v[192:195], v157 offset:17408
	ds_read_b128 v[196:199], v157 offset:18432
	ds_read_b128 v[200:203], v157 offset:19456
	ds_read_b128 v[204:207], v157 offset:20480
	ds_read_b128 v[208:211], v157 offset:21504
	ds_read_b128 v[212:215], v157 offset:22528
	ds_read_b128 v[216:219], v157 offset:23552
	global_load_lds_dwordx4 v[220:221], off
	s_add_i32 m0, s62, 0x2000
	s_add_u32 s94, s78, 0x160000
	v_lshl_add_u64 v[222:223], s[78:79], 0, v[134:135]
	s_addc_u32 s95, s79, 0
	s_add_i32 s62, s87, s35
	global_load_lds_dwordx4 v[222:223], off
	v_lshl_add_u64 v[224:225], s[94:95], 0, v[130:131]
	s_mov_b32 m0, s62
	v_lshl_add_u64 v[226:227], s[80:81], 0, v[132:133]
	global_load_lds_dwordx4 v[224:225], off
	v_lshl_add_u64 v[224:225], s[94:95], 0, v[134:135]
	s_add_i32 m0, s62, 0x2000
	s_nop 0
	global_load_lds_dwordx4 v[224:225], off
	v_lshl_add_u64 v[224:225], s[80:81], 0, v[128:129]
	s_mov_b32 m0, s52
	s_nop 0
	global_load_lds_dwordx4 v[224:225], off
	s_mov_b32 m0, s53
	s_nop 0
	global_load_lds_dwordx4 v[226:227], off
	s_waitcnt vmcnt(8)
	s_waitcnt lgkmcnt(0)
	s_setprio 1
	s_barrier
; #define PG8_STAGE(bufoff, gbase, voff) do { _Pragma("unroll") for (int _i = 0; _i < 2; ++_i) \
;         __builtin_amdgcn_global_load_lds((const unsigned*)((const char*)(gbase) + (voff)[_i]), (PG8_LAS unsigned*)(lds + (bufoff) + ldsw + _i * 8192), 16, 0, 0); } while (0)
; #define PG8_LDA(dst, b, h) do { _Pragma("unroll") for (int m = 0; m < 4; ++m) _Pragma("unroll") for (int k = 0; k < 2; ++k) dst[m][k] = *(const PG8_LAS bf16x8*)(lds + PG8_SA(b, h) + aoff + m * 2048 + k * 1024); } while (0)
; #define PG8_LDB(dst, b, h) do { _Pragma("unroll") for (int n = 0; n < 2; ++n) _Pragma("unroll") for (int k = 0; k < 2; ++k) dst[n][k] = *(const PG8_LAS bf16x8*)(lds + PG8_SB(b, h) + boff + n * 2048 + k * 1024); } while (0)
; #define PG8_MMA(ai, bj, At, Bt) do { __builtin_amdgcn_s_setprio(1); _Pragma("unroll") for (int m = 0; m < 4; ++m) _Pragma("unroll") for (int n = 0; n < 2; ++n) _Pragma("unroll") for (int k = 0; k < 2; ++k) \
;         acc[ai][bj][m][n] = __builtin_amdgcn_mfma_f32_16x16x32_bf16(Bt[n][k], At[m][k], acc[ai][bj][m][n], 0, 0, 0); __builtin_amdgcn_s_setprio(0); } while (0)
; #define PG8_WAIT_V(n) asm volatile("s_waitcnt vmcnt(" #n ")" ::: "memory")
; #define PG8_WAIT_L(n) asm volatile("s_waitcnt lgkmcnt(" #n ")" ::: "memory")
; #define PG8_BAR __builtin_amdgcn_s_barrier()
; #define PG8_SCHED __builtin_amdgcn_sched_barrier(0)
; template <class Epi, class Sched, bool ALIGN_EPI = false, bool SP2 = false>
; __device__ __forceinline__ void gemm_phase(PG8_LAS unsigned char* lds, const Gemm g, const Sched& S, const Epi& E) {
;     ...
;             PG8_WAIT_V(8); PG8_WAIT_L(0); PG8_BAR; PG8_MMA(1, 0, At, B0); PG8_MMA(1, 1, At, B1); PG8_BAR; PG8_SCHED;
;             PG8_LDB(B0, 1, 0); PG8_LDB(B1, 1, 1); PG8_SCHED; PG8_LDA(At, 1, 0); PG8_STAGE(PG8_SA(0, 1), a2 + hstep, voffA);
;             PG8_WAIT_V(8); PG8_WAIT_L(0); PG8_BAR; PG8_MMA(0, 0, At, B0); PG8_MMA(0, 1, At, B1); PG8_BAR; PG8_SCHED;
	v_mfma_f32_16x16x32_bf16 v[60:63], v[144:147], v[188:191], v[60:63]
	v_mfma_f32_16x16x32_bf16 v[60:63], v[160:163], v[192:195], v[60:63]
	v_mfma_f32_16x16x32_bf16 v[44:47], v[144:147], v[196:199], v[44:47]
	v_mfma_f32_16x16x32_bf16 v[44:47], v[160:163], v[200:203], v[44:47]
	v_mfma_f32_16x16x32_bf16 v[28:31], v[144:147], v[204:207], v[28:31]
	v_mfma_f32_16x16x32_bf16 v[28:31], v[160:163], v[208:211], v[28:31]
	v_mfma_f32_16x16x32_bf16 v[12:15], v[144:147], v[212:215], v[12:15]
	v_mfma_f32_16x16x32_bf16 v[12:15], v[160:163], v[216:219], v[12:15]
	v_mfma_f32_16x16x32_bf16 v[8:11], v[164:167], v[212:215], v[8:11]
	v_mfma_f32_16x16x32_bf16 v[8:11], v[168:171], v[216:219], v[8:11]
	v_mfma_f32_16x16x32_bf16 v[24:27], v[164:167], v[204:207], v[24:27]
	v_mfma_f32_16x16x32_bf16 v[24:27], v[168:171], v[208:211], v[24:27]
	v_mfma_f32_16x16x32_bf16 v[40:43], v[164:167], v[196:199], v[40:43]
	v_mfma_f32_16x16x32_bf16 v[40:43], v[168:171], v[200:203], v[40:43]
	v_mfma_f32_16x16x32_bf16 v[56:59], v[164:167], v[188:191], v[56:59]
	v_mfma_f32_16x16x32_bf16 v[56:59], v[168:171], v[192:195], v[56:59]
	v_mfma_f32_16x16x32_bf16 v[52:55], v[172:175], v[188:191], v[52:55]
	v_mfma_f32_16x16x32_bf16 v[52:55], v[176:179], v[192:195], v[52:55]
	v_mfma_f32_16x16x32_bf16 v[36:39], v[172:175], v[196:199], v[36:39]
	v_mfma_f32_16x16x32_bf16 v[36:39], v[176:179], v[200:203], v[36:39]
	v_mfma_f32_16x16x32_bf16 v[20:23], v[172:175], v[204:207], v[20:23]
	v_mfma_f32_16x16x32_bf16 v[20:23], v[176:179], v[208:211], v[20:23]
	v_mfma_f32_16x16x32_bf16 v[4:7], v[172:175], v[212:215], v[4:7]
	v_mfma_f32_16x16x32_bf16 v[4:7], v[176:179], v[216:219], v[4:7]
	v_mfma_f32_16x16x32_bf16 v[0:3], v[180:183], v[212:215], v[0:3]
	v_mfma_f32_16x16x32_bf16 v[0:3], v[184:187], v[216:219], v[0:3]
	v_mfma_f32_16x16x32_bf16 v[16:19], v[180:183], v[204:207], v[16:19]
	v_mfma_f32_16x16x32_bf16 v[16:19], v[184:187], v[208:211], v[16:19]
	s_setprio 2
	s_barrier
	v_mfma_f32_16x16x32_bf16 v[32:35], v[180:183], v[196:199], v[32:35]
	v_mfma_f32_16x16x32_bf16 v[32:35], v[184:187], v[200:203], v[32:35]
	v_mfma_f32_16x16x32_bf16 v[48:51], v[180:183], v[188:191], v[48:51]
	v_mfma_f32_16x16x32_bf16 v[48:51], v[184:187], v[192:195], v[48:51]
	s_setprio 0
	s_add_i32 s62, 0, 0x18000
	v_add_u32_e32 v159, s62, v153
	s_add_i32 s63, 0, 0x1c000
	ds_read_b128 v[144:147], v159
	ds_read_b128 v[160:163], v159 offset:1024
	ds_read_b128 v[164:167], v159 offset:2048
	ds_read_b128 v[168:171], v159 offset:3072
	v_add_u32_e32 v159, s63, v153
	ds_read_b128 v[172:175], v159
	ds_read_b128 v[176:179], v159 offset:1024
	ds_read_b128 v[180:183], v159 offset:2048
	ds_read_b128 v[184:187], v159 offset:3072
	s_add_u32 s80, s80, 0x160000
	s_addc_u32 s81, s81, 0
	s_mov_b32 m0, s61
	v_lshl_add_u64 v[228:229], s[80:81], 0, v[128:129]
	ds_read_b128 v[188:191], v157 offset:32768
	ds_read_b128 v[192:195], v157 offset:33792
	ds_read_b128 v[196:199], v157 offset:34816
	ds_read_b128 v[200:203], v157 offset:35840
	ds_read_b128 v[204:207], v157 offset:36864
	ds_read_b128 v[208:211], v157 offset:37888
	ds_read_b128 v[212:215], v157 offset:38912
	ds_read_b128 v[216:219], v157 offset:39936
	global_load_lds_dwordx4 v[228:229], off
	v_lshl_add_u64 v[228:229], s[80:81], 0, v[132:133]
	s_mov_b32 m0, s65
	s_nop 0
	global_load_lds_dwordx4 v[228:229], off
	s_waitcnt vmcnt(8)
	s_waitcnt lgkmcnt(0)
	s_setprio 1
	s_barrier
	v_mfma_f32_16x16x32_bf16 v[124:127], v[144:147], v[188:191], v[124:127]
	v_mfma_f32_16x16x32_bf16 v[124:127], v[160:163], v[192:195], v[124:127]
	v_mfma_f32_16x16x32_bf16 v[108:111], v[144:147], v[196:199], v[108:111]
	v_mfma_f32_16x16x32_bf16 v[108:111], v[160:163], v[200:203], v[108:111]
	v_mfma_f32_16x16x32_bf16 v[92:95], v[144:147], v[204:207], v[92:95]
	v_mfma_f32_16x16x32_bf16 v[92:95], v[160:163], v[208:211], v[92:95]
	v_mfma_f32_16x16x32_bf16 v[76:79], v[144:147], v[212:215], v[76:79]
	v_mfma_f32_16x16x32_bf16 v[76:79], v[160:163], v[216:219], v[76:79]
	v_mfma_f32_16x16x32_bf16 v[72:75], v[164:167], v[212:215], v[72:75]
	v_mfma_f32_16x16x32_bf16 v[72:75], v[168:171], v[216:219], v[72:75]
	v_mfma_f32_16x16x32_bf16 v[88:91], v[164:167], v[204:207], v[88:91]
	v_mfma_f32_16x16x32_bf16 v[88:91], v[168:171], v[208:211], v[88:91]
	v_mfma_f32_16x16x32_bf16 v[104:107], v[164:167], v[196:199], v[104:107]
	v_mfma_f32_16x16x32_bf16 v[104:107], v[168:171], v[200:203], v[104:107]
	v_mfma_f32_16x16x32_bf16 v[120:123], v[164:167], v[188:191], v[120:123]
	v_mfma_f32_16x16x32_bf16 v[120:123], v[168:171], v[192:195], v[120:123]
	v_mfma_f32_16x16x32_bf16 v[116:119], v[172:175], v[188:191], v[116:119]
	v_mfma_f32_16x16x32_bf16 v[116:119], v[176:179], v[192:195], v[116:119]
	v_mfma_f32_16x16x32_bf16 v[100:103], v[172:175], v[196:199], v[100:103]
	v_mfma_f32_16x16x32_bf16 v[100:103], v[176:179], v[200:203], v[100:103]
	v_mfma_f32_16x16x32_bf16 v[84:87], v[172:175], v[204:207], v[84:87]
	v_mfma_f32_16x16x32_bf16 v[84:87], v[176:179], v[208:211], v[84:87]
	v_mfma_f32_16x16x32_bf16 v[68:71], v[172:175], v[212:215], v[68:71]
	v_mfma_f32_16x16x32_bf16 v[68:71], v[176:179], v[216:219], v[68:71]
	v_mfma_f32_16x16x32_bf16 v[64:67], v[180:183], v[212:215], v[64:67]
	v_mfma_f32_16x16x32_bf16 v[64:67], v[184:187], v[216:219], v[64:67]
	v_mfma_f32_16x16x32_bf16 v[80:83], v[180:183], v[204:207], v[80:83]
	v_mfma_f32_16x16x32_bf16 v[80:83], v[184:187], v[208:211], v[80:83]
	s_setprio 2
	s_barrier
; #define PG8_STAGE(bufoff, gbase, voff) do { _Pragma("unroll") for (int _i = 0; _i < 2; ++_i) \
;         __builtin_amdgcn_global_load_lds((const unsigned*)((const char*)(gbase) + (voff)[_i]), (PG8_LAS unsigned*)(lds + (bufoff) + ldsw + _i * 8192), 16, 0, 0); } while (0)
; #define PG8_LDA(dst, b, h) do { _Pragma("unroll") for (int m = 0; m < 4; ++m) _Pragma("unroll") for (int k = 0; k < 2; ++k) dst[m][k] = *(const PG8_LAS bf16x8*)(lds + PG8_SA(b, h) + aoff + m * 2048 + k * 1024); } while (0)
; #define PG8_MMA(ai, bj, At, Bt) do { __builtin_amdgcn_s_setprio(1); _Pragma("unroll") for (int m = 0; m < 4; ++m) _Pragma("unroll") for (int n = 0; n < 2; ++n) _Pragma("unroll") for (int k = 0; k < 2; ++k) \
;         acc[ai][bj][m][n] = __builtin_amdgcn_mfma_f32_16x16x32_bf16(Bt[n][k], At[m][k], acc[ai][bj][m][n], 0, 0, 0); __builtin_amdgcn_s_setprio(0); } while (0)
; #define PG8_WAIT_V(n) asm volatile("s_waitcnt vmcnt(" #n ")" ::: "memory")
; #define PG8_WAIT_L(n) asm volatile("s_waitcnt lgkmcnt(" #n ")" ::: "memory")
; #define PG8_BAR __builtin_amdgcn_s_barrier()
; #define PG8_SCHED __builtin_amdgcn_sched_barrier(0)
; template <class Epi, class Sched, bool ALIGN_EPI = false, bool SP2 = false>
; __device__ __forceinline__ void gemm_phase(PG8_LAS unsigned char* lds, const Gemm g, const Sched& S, const Epi& E) {
;     ...
;             PG8_LDA(At, 1, 1); PG8_STAGE(PG8_SB(1, 0), b3, voffB); PG8_STAGE(PG8_SB(1, 1), b3 + hstep, voffB); PG8_STAGE(PG8_SA(1, 0), a3, voffA);
;             PG8_WAIT_V(8); PG8_WAIT_L(0); PG8_BAR; PG8_MMA(1, 0, At, B0); PG8_MMA(1, 1, At, B1); PG8_BAR; PG8_SCHED;
;     ...
;         if constexpr (ALIGN_EPI) { if (wr == 0) PG8_BAR; }
	v_mfma_f32_16x16x32_bf16 v[96:99], v[180:183], v[196:199], v[96:99]
	v_mfma_f32_16x16x32_bf16 v[96:99], v[184:187], v[200:203], v[96:99]
	v_mfma_f32_16x16x32_bf16 v[112:115], v[180:183], v[188:191], v[112:115]
	v_mfma_f32_16x16x32_bf16 v[112:115], v[184:187], v[192:195], v[112:115]
	s_setprio 0
	s_add_i32 s62, s62, s35
	v_lshl_add_u64 v[220:221], v[220:221], 0, s[56:57]
	s_mov_b32 m0, s62
	ds_read_b128 v[188:191], v157 offset:49152
	ds_read_b128 v[192:195], v157 offset:50176
	ds_read_b128 v[196:199], v157 offset:51200
	ds_read_b128 v[200:203], v157 offset:52224
	ds_read_b128 v[204:207], v157 offset:53248
	ds_read_b128 v[208:211], v157 offset:54272
	ds_read_b128 v[212:215], v157 offset:55296
	ds_read_b128 v[216:219], v157 offset:56320
	global_load_lds_dwordx4 v[220:221], off
	s_add_i32 m0, s62, 0x2000
	s_add_u32 s78, s78, 0x160080
	v_lshl_add_u64 v[220:221], v[222:223], 0, s[56:57]
	s_addc_u32 s79, s79, 0
	s_add_i32 s62, s63, s35
	global_load_lds_dwordx4 v[220:221], off
	v_lshl_add_u64 v[220:221], s[78:79], 0, v[130:131]
	s_mov_b32 m0, s62
	s_nop 0
	global_load_lds_dwordx4 v[220:221], off
	v_lshl_add_u64 v[220:221], s[78:79], 0, v[134:135]
	s_add_i32 m0, s62, 0x2000
	s_nop 0
	global_load_lds_dwordx4 v[220:221], off
	v_lshl_add_u64 v[220:221], v[224:225], 0, s[56:57]
	s_mov_b32 m0, s83
	s_nop 0
	global_load_lds_dwordx4 v[220:221], off
	v_lshl_add_u64 v[220:221], v[226:227], 0, s[56:57]
	s_mov_b32 m0, s84
	s_nop 0
	global_load_lds_dwordx4 v[220:221], off
	s_waitcnt vmcnt(8)
	s_waitcnt lgkmcnt(0)
	s_setprio 1
	s_barrier
	v_mfma_f32_16x16x32_bf16 v[60:63], v[144:147], v[188:191], v[60:63]
	v_mfma_f32_16x16x32_bf16 v[60:63], v[160:163], v[192:195], v[60:63]
	v_mfma_f32_16x16x32_bf16 v[44:47], v[144:147], v[196:199], v[44:47]
	v_mfma_f32_16x16x32_bf16 v[44:47], v[160:163], v[200:203], v[44:47]
	v_mfma_f32_16x16x32_bf16 v[28:31], v[144:147], v[204:207], v[28:31]
	v_mfma_f32_16x16x32_bf16 v[28:31], v[160:163], v[208:211], v[28:31]
	v_mfma_f32_16x16x32_bf16 v[12:15], v[144:147], v[212:215], v[12:15]
	v_mfma_f32_16x16x32_bf16 v[12:15], v[160:163], v[216:219], v[12:15]
	v_mfma_f32_16x16x32_bf16 v[8:11], v[164:167], v[212:215], v[8:11]
	v_mfma_f32_16x16x32_bf16 v[8:11], v[168:171], v[216:219], v[8:11]
	v_mfma_f32_16x16x32_bf16 v[24:27], v[164:167], v[204:207], v[24:27]
	v_mfma_f32_16x16x32_bf16 v[24:27], v[168:171], v[208:211], v[24:27]
	v_mfma_f32_16x16x32_bf16 v[40:43], v[164:167], v[196:199], v[40:43]
	v_mfma_f32_16x16x32_bf16 v[40:43], v[168:171], v[200:203], v[40:43]
	v_mfma_f32_16x16x32_bf16 v[56:59], v[164:167], v[188:191], v[56:59]
	v_mfma_f32_16x16x32_bf16 v[56:59], v[168:171], v[192:195], v[56:59]
	v_mfma_f32_16x16x32_bf16 v[52:55], v[172:175], v[188:191], v[52:55]
	v_mfma_f32_16x16x32_bf16 v[52:55], v[176:179], v[192:195], v[52:55]
	v_mfma_f32_16x16x32_bf16 v[36:39], v[172:175], v[196:199], v[36:39]
	v_mfma_f32_16x16x32_bf16 v[36:39], v[176:179], v[200:203], v[36:39]
	v_mfma_f32_16x16x32_bf16 v[20:23], v[172:175], v[204:207], v[20:23]
	v_mfma_f32_16x16x32_bf16 v[20:23], v[176:179], v[208:211], v[20:23]
	v_mfma_f32_16x16x32_bf16 v[4:7], v[172:175], v[212:215], v[4:7]
	v_mfma_f32_16x16x32_bf16 v[4:7], v[176:179], v[216:219], v[4:7]
	v_mfma_f32_16x16x32_bf16 v[0:3], v[180:183], v[212:215], v[0:3]
	v_mfma_f32_16x16x32_bf16 v[0:3], v[184:187], v[216:219], v[0:3]
	v_mfma_f32_16x16x32_bf16 v[16:19], v[180:183], v[204:207], v[16:19]
	v_mfma_f32_16x16x32_bf16 v[16:19], v[184:187], v[208:211], v[16:19]
	s_setprio 2
	s_barrier
	v_mfma_f32_16x16x32_bf16 v[32:35], v[180:183], v[196:199], v[32:35]
	v_mfma_f32_16x16x32_bf16 v[32:35], v[184:187], v[200:203], v[32:35]
	v_mfma_f32_16x16x32_bf16 v[48:51], v[180:183], v[188:191], v[48:51]
	v_mfma_f32_16x16x32_bf16 v[48:51], v[184:187], v[192:195], v[48:51]
	s_setprio 0
	s_add_i32 s92, s92, 2
	s_add_u32 s76, s76, 0x100
	s_addc_u32 s77, s77, 0
	s_add_u32 s50, s50, 0x100
	s_addc_u32 s91, s91, 0
	s_cmpk_gt_u32 s92, 0x55
	s_cbranch_scc0 .LBB0_179
	s_and_b64 vcc, exec, s[58:59]
	s_cbranch_vccz .LBB0_182
	s_barrier

; #define PG8_STAGE(bufoff, gbase, voff) do { _Pragma("unroll") for (int _i = 0; _i < 2; ++_i) \
;         __builtin_amdgcn_global_load_lds((const unsigned*)((const char*)(gbase) + (voff)[_i]), (PG8_LAS unsigned*)(lds + (bufoff) + ldsw + _i * 8192), 16, 0, 0); } while (0)
; #define PG8_LDA(dst, b, h) do { _Pragma("unroll") for (int m = 0; m < 4; ++m) _Pragma("unroll") for (int k = 0; k < 2; ++k) dst[m][k] = *(const PG8_LAS bf16x8*)(lds + PG8_SA(b, h) + aoff + m * 2048 + k * 1024); } while (0)
; #define PG8_LDB(dst, b, h) do { _Pragma("unroll") for (int n = 0; n < 2; ++n) _Pragma("unroll") for (int k = 0; k < 2; ++k) dst[n][k] = *(const PG8_LAS bf16x8*)(lds + PG8_SB(b, h) + boff + n * 2048 + k * 1024); } while (0)
; #define PG8_MMA(ai, bj, At, Bt) do { __builtin_amdgcn_s_setprio(1); _Pragma("unroll") for (int m = 0; m < 4; ++m) _Pragma("unroll") for (int n = 0; n < 2; ++n) _Pragma("unroll") for (int k = 0; k < 2; ++k) \
;         acc[ai][bj][m][n] = __builtin_amdgcn_mfma_f32_16x16x32_bf16(Bt[n][k], At[m][k], acc[ai][bj][m][n], 0, 0, 0); __builtin_amdgcn_s_setprio(0); } while (0)
; #define PG8_WAIT_V(n) asm volatile("s_waitcnt vmcnt(" #n ")" ::: "memory")
; #define PG8_WAIT_L(n) asm volatile("s_waitcnt lgkmcnt(" #n ")" ::: "memory")
; #define PG8_BAR __builtin_amdgcn_s_barrier()
; #define PG8_SCHED __builtin_amdgcn_sched_barrier(0)
; template <class Epi, class Sched, bool ALIGN_EPI = false, bool SP2 = false>
; __device__ __forceinline__ void gemm_phase(PG8_LAS unsigned char* lds, const Gemm g, const Sched& S, const Epi& E) {
;     ...
;             PG8_LDB(B0, 0, 0); PG8_LDB(B1, 0, 1); PG8_SCHED; PG8_LDA(At, 0, 0); PG8_STAGE(PG8_SA(1, 1), a1 + hstep, voffA);
;             PG8_WAIT_V(8); PG8_WAIT_L(0); PG8_BAR; PG8_MMA(0, 0, At, B0); PG8_MMA(0, 1, At, B1); PG8_BAR; PG8_SCHED;
;             PG8_LDA(At, 0, 1); PG8_STAGE(PG8_SB(0, 0), b2, voffB); PG8_STAGE(PG8_SB(0, 1), b2 + hstep, voffB); PG8_STAGE(PG8_SA(0, 0), a2, voffA);
;             PG8_WAIT_V(8); PG8_WAIT_L(0); PG8_BAR; PG8_MMA(1, 0, At, B0); PG8_MMA(1, 1, At, B1); PG8_BAR; PG8_SCHED;
.LBB0_326:
	ds_read_b128 v[178:181], v176
	ds_read_b128 v[182:185], v176 offset:1024
	ds_read_b128 v[186:189], v176 offset:2048
	ds_read_b128 v[190:193], v176 offset:3072
	ds_read_b128 v[194:197], v177
	ds_read_b128 v[198:201], v177 offset:1024
	ds_read_b128 v[202:205], v177 offset:2048
	ds_read_b128 v[206:209], v177 offset:3072
	s_add_u32 s62, s76, 0xfff80080
	s_addc_u32 s63, s77, -1
	s_cmp_eq_u32 s75, 28
	s_cselect_b32 s81, s10, s63
	s_cselect_b32 s80, s11, s62
	s_cselect_b32 s79, s51, s67
	s_cselect_b32 s78, s55, s57
	v_lshl_add_u64 v[166:167], s[76:77], 0, v[146:147]
	s_add_i32 m0, s64, 0xc000
	ds_read_b128 v[210:213], v145
	ds_read_b128 v[214:217], v145 offset:1024
	ds_read_b128 v[218:221], v145 offset:2048
	ds_read_b128 v[222:225], v145 offset:3072
	ds_read_b128 v[226:229], v145 offset:4096
	ds_read_b128 v[230:233], v145 offset:5120
	ds_read_b128 v[234:237], v145 offset:6144
	ds_read_b128 v[238:241], v145 offset:7168
	global_load_lds_dwordx4 v[166:167], off
	v_lshl_add_u64 v[166:167], s[76:77], 0, v[152:153]
	s_add_i32 m0, s64, 0xe000
	s_nop 0
	global_load_lds_dwordx4 v[166:167], off
	s_waitcnt vmcnt(8)
	s_waitcnt lgkmcnt(0)
	s_setprio 1
	s_barrier
	v_mfma_f32_16x16x32_bf16 v[124:127], v[178:181], v[210:213], v[124:127]
	v_mfma_f32_16x16x32_bf16 v[124:127], v[182:185], v[214:217], v[124:127]
	v_mfma_f32_16x16x32_bf16 v[116:119], v[178:181], v[218:221], v[116:119]
	v_mfma_f32_16x16x32_bf16 v[116:119], v[182:185], v[222:225], v[116:119]
	v_mfma_f32_16x16x32_bf16 v[108:111], v[178:181], v[226:229], v[108:111]
	v_mfma_f32_16x16x32_bf16 v[108:111], v[182:185], v[230:233], v[108:111]
	v_mfma_f32_16x16x32_bf16 v[100:103], v[178:181], v[234:237], v[100:103]
	v_mfma_f32_16x16x32_bf16 v[100:103], v[182:185], v[238:241], v[100:103]
	v_mfma_f32_16x16x32_bf16 v[96:99], v[186:189], v[234:237], v[96:99]
	v_mfma_f32_16x16x32_bf16 v[96:99], v[190:193], v[238:241], v[96:99]
	v_mfma_f32_16x16x32_bf16 v[104:107], v[186:189], v[226:229], v[104:107]
	v_mfma_f32_16x16x32_bf16 v[104:107], v[190:193], v[230:233], v[104:107]
	v_mfma_f32_16x16x32_bf16 v[112:115], v[186:189], v[218:221], v[112:115]
	v_mfma_f32_16x16x32_bf16 v[112:115], v[190:193], v[222:225], v[112:115]
	v_mfma_f32_16x16x32_bf16 v[120:123], v[186:189], v[210:213], v[120:123]
	v_mfma_f32_16x16x32_bf16 v[120:123], v[190:193], v[214:217], v[120:123]
	v_mfma_f32_16x16x32_bf16 v[68:71], v[194:197], v[210:213], v[68:71]
	v_mfma_f32_16x16x32_bf16 v[68:71], v[198:201], v[214:217], v[68:71]
	v_mfma_f32_16x16x32_bf16 v[52:55], v[194:197], v[218:221], v[52:55]
	v_mfma_f32_16x16x32_bf16 v[52:55], v[198:201], v[222:225], v[52:55]
	v_mfma_f32_16x16x32_bf16 v[44:47], v[194:197], v[226:229], v[44:47]
	v_mfma_f32_16x16x32_bf16 v[44:47], v[198:201], v[230:233], v[44:47]
	v_mfma_f32_16x16x32_bf16 v[36:39], v[194:197], v[234:237], v[36:39]
	v_mfma_f32_16x16x32_bf16 v[36:39], v[198:201], v[238:241], v[36:39]
	v_mfma_f32_16x16x32_bf16 v[32:35], v[202:205], v[234:237], v[32:35]
	v_mfma_f32_16x16x32_bf16 v[32:35], v[206:209], v[238:241], v[32:35]
	v_mfma_f32_16x16x32_bf16 v[40:43], v[202:205], v[226:229], v[40:43]
	v_mfma_f32_16x16x32_bf16 v[40:43], v[206:209], v[230:233], v[40:43]
	s_setprio 2
	s_barrier
	v_mfma_f32_16x16x32_bf16 v[48:51], v[202:205], v[218:221], v[48:51]
	v_mfma_f32_16x16x32_bf16 v[48:51], v[206:209], v[222:225], v[48:51]
	v_mfma_f32_16x16x32_bf16 v[64:67], v[202:205], v[210:213], v[64:67]
	v_mfma_f32_16x16x32_bf16 v[64:67], v[206:209], v[214:217], v[64:67]
	s_setprio 0
	s_add_i32 s62, s53, s3
	v_lshl_add_u64 v[166:167], s[78:79], 0, v[130:131]
	s_mov_b32 m0, s62
	ds_read_b128 v[210:213], v145 offset:16384
	ds_read_b128 v[214:217], v145 offset:17408
	ds_read_b128 v[218:221], v145 offset:18432
	ds_read_b128 v[222:225], v145 offset:19456
	ds_read_b128 v[226:229], v145 offset:20480
	ds_read_b128 v[230:233], v145 offset:21504
	ds_read_b128 v[234:237], v145 offset:22528
	ds_read_b128 v[238:241], v145 offset:23552
	global_load_lds_dwordx4 v[166:167], off
	s_add_i32 m0, s62, 0x2000
	s_add_u32 s82, s78, 0x80000
	v_lshl_add_u64 v[242:243], s[78:79], 0, v[134:135]
	s_addc_u32 s83, s79, 0
	s_add_i32 s62, s66, s3
	global_load_lds_dwordx4 v[242:243], off
	v_lshl_add_u64 v[244:245], s[82:83], 0, v[130:131]
	s_mov_b32 m0, s62
	v_lshl_add_u64 v[246:247], s[80:81], 0, v[132:133]
	global_load_lds_dwordx4 v[244:245], off
	v_lshl_add_u64 v[244:245], s[82:83], 0, v[134:135]
	s_add_i32 m0, s62, 0x2000
	s_nop 0
	global_load_lds_dwordx4 v[244:245], off
	v_lshl_add_u64 v[244:245], s[80:81], 0, v[128:129]
	s_mov_b32 m0, s64
	s_nop 0
	global_load_lds_dwordx4 v[244:245], off
	s_mov_b32 m0, s65
	s_nop 0
	global_load_lds_dwordx4 v[246:247], off
	s_waitcnt vmcnt(8)
	s_waitcnt lgkmcnt(0)
	s_setprio 1
	s_barrier
; #define PG8_STAGE(bufoff, gbase, voff) do { _Pragma("unroll") for (int _i = 0; _i < 2; ++_i) \
;         __builtin_amdgcn_global_load_lds((const unsigned*)((const char*)(gbase) + (voff)[_i]), (PG8_LAS unsigned*)(lds + (bufoff) + ldsw + _i * 8192), 16, 0, 0); } while (0)
; #define PG8_LDA(dst, b, h) do { _Pragma("unroll") for (int m = 0; m < 4; ++m) _Pragma("unroll") for (int k = 0; k < 2; ++k) dst[m][k] = *(const PG8_LAS bf16x8*)(lds + PG8_SA(b, h) + aoff + m * 2048 + k * 1024); } while (0)
; #define PG8_LDB(dst, b, h) do { _Pragma("unroll") for (int n = 0; n < 2; ++n) _Pragma("unroll") for (int k = 0; k < 2; ++k) dst[n][k] = *(const PG8_LAS bf16x8*)(lds + PG8_SB(b, h) + boff + n * 2048 + k * 1024); } while (0)
; #define PG8_MMA(ai, bj, At, Bt) do { __builtin_amdgcn_s_setprio(1); _Pragma("unroll") for (int m = 0; m < 4; ++m) _Pragma("unroll") for (int n = 0; n < 2; ++n) _Pragma("unroll") for (int k = 0; k < 2; ++k) \
;         acc[ai][bj][m][n] = __builtin_amdgcn_mfma_f32_16x16x32_bf16(Bt[n][k], At[m][k], acc[ai][bj][m][n], 0, 0, 0); __builtin_amdgcn_s_setprio(0); } while (0)
; #define PG8_WAIT_V(n) asm volatile("s_waitcnt vmcnt(" #n ")" ::: "memory")
; #define PG8_WAIT_L(n) asm volatile("s_waitcnt lgkmcnt(" #n ")" ::: "memory")
; #define PG8_BAR __builtin_amdgcn_s_barrier()
; #define PG8_SCHED __builtin_amdgcn_sched_barrier(0)
; template <class Epi, class Sched, bool ALIGN_EPI = false, bool SP2 = false>
; __device__ __forceinline__ void gemm_phase(PG8_LAS unsigned char* lds, const Gemm g, const Sched& S, const Epi& E) {
;     ...
;             PG8_WAIT_V(8); PG8_WAIT_L(0); PG8_BAR; PG8_MMA(1, 0, At, B0); PG8_MMA(1, 1, At, B1); PG8_BAR; PG8_SCHED;
;             PG8_LDB(B0, 1, 0); PG8_LDB(B1, 1, 1); PG8_SCHED; PG8_LDA(At, 1, 0); PG8_STAGE(PG8_SA(0, 1), a2 + hstep, voffA);
;             PG8_WAIT_V(8); PG8_WAIT_L(0); PG8_BAR; PG8_MMA(0, 0, At, B0); PG8_MMA(0, 1, At, B1); PG8_BAR; PG8_SCHED;
	v_mfma_f32_16x16x32_bf16 v[92:95], v[178:181], v[210:213], v[92:95]
	v_mfma_f32_16x16x32_bf16 v[92:95], v[182:185], v[214:217], v[92:95]
	v_mfma_f32_16x16x32_bf16 v[84:87], v[178:181], v[218:221], v[84:87]
	v_mfma_f32_16x16x32_bf16 v[84:87], v[182:185], v[222:225], v[84:87]
	v_mfma_f32_16x16x32_bf16 v[76:79], v[178:181], v[226:229], v[76:79]
	v_mfma_f32_16x16x32_bf16 v[76:79], v[182:185], v[230:233], v[76:79]
	v_mfma_f32_16x16x32_bf16 v[60:63], v[178:181], v[234:237], v[60:63]
	v_mfma_f32_16x16x32_bf16 v[60:63], v[182:185], v[238:241], v[60:63]
	v_mfma_f32_16x16x32_bf16 v[56:59], v[186:189], v[234:237], v[56:59]
	v_mfma_f32_16x16x32_bf16 v[56:59], v[190:193], v[238:241], v[56:59]
	v_mfma_f32_16x16x32_bf16 v[72:75], v[186:189], v[226:229], v[72:75]
	v_mfma_f32_16x16x32_bf16 v[72:75], v[190:193], v[230:233], v[72:75]
	v_mfma_f32_16x16x32_bf16 v[80:83], v[186:189], v[218:221], v[80:83]
	v_mfma_f32_16x16x32_bf16 v[80:83], v[190:193], v[222:225], v[80:83]
	v_mfma_f32_16x16x32_bf16 v[88:91], v[186:189], v[210:213], v[88:91]
	v_mfma_f32_16x16x32_bf16 v[88:91], v[190:193], v[214:217], v[88:91]
	v_mfma_f32_16x16x32_bf16 v[28:31], v[194:197], v[210:213], v[28:31]
	v_mfma_f32_16x16x32_bf16 v[28:31], v[198:201], v[214:217], v[28:31]
	v_mfma_f32_16x16x32_bf16 v[20:23], v[194:197], v[218:221], v[20:23]
	v_mfma_f32_16x16x32_bf16 v[20:23], v[198:201], v[222:225], v[20:23]
	v_mfma_f32_16x16x32_bf16 v[12:15], v[194:197], v[226:229], v[12:15]
	v_mfma_f32_16x16x32_bf16 v[12:15], v[198:201], v[230:233], v[12:15]
	v_mfma_f32_16x16x32_bf16 v[4:7], v[194:197], v[234:237], v[4:7]
	v_mfma_f32_16x16x32_bf16 v[4:7], v[198:201], v[238:241], v[4:7]
	v_mfma_f32_16x16x32_bf16 v[0:3], v[202:205], v[234:237], v[0:3]
	v_mfma_f32_16x16x32_bf16 v[0:3], v[206:209], v[238:241], v[0:3]
	v_mfma_f32_16x16x32_bf16 v[8:11], v[202:205], v[226:229], v[8:11]
	v_mfma_f32_16x16x32_bf16 v[8:11], v[206:209], v[230:233], v[8:11]
	s_setprio 2
	s_barrier
	v_mfma_f32_16x16x32_bf16 v[16:19], v[202:205], v[218:221], v[16:19]
	v_mfma_f32_16x16x32_bf16 v[16:19], v[206:209], v[222:225], v[16:19]
	v_mfma_f32_16x16x32_bf16 v[24:27], v[202:205], v[210:213], v[24:27]
	v_mfma_f32_16x16x32_bf16 v[24:27], v[206:209], v[214:217], v[24:27]
	s_setprio 0
	s_add_i32 s62, 0, 0x18000
	s_add_i32 s63, 0, 0x1c000
	v_add_u32_e32 v190, s62, v143
	v_add_u32_e32 v206, s63, v143
	ds_read_b128 v[178:181], v190
	ds_read_b128 v[182:185], v190 offset:1024
	ds_read_b128 v[186:189], v190 offset:2048
	ds_read_b128 v[190:193], v190 offset:3072
	ds_read_b128 v[194:197], v206
	ds_read_b128 v[198:201], v206 offset:1024
	ds_read_b128 v[202:205], v206 offset:2048
	ds_read_b128 v[206:209], v206 offset:3072
	s_add_u32 s80, s80, 0x80000
	s_addc_u32 s81, s81, 0
	s_mov_b32 m0, s86
	v_lshl_add_u64 v[248:249], s[80:81], 0, v[128:129]
	ds_read_b128 v[210:213], v145 offset:32768
	ds_read_b128 v[214:217], v145 offset:33792
	ds_read_b128 v[218:221], v145 offset:34816
	ds_read_b128 v[222:225], v145 offset:35840
	ds_read_b128 v[226:229], v145 offset:36864
	ds_read_b128 v[230:233], v145 offset:37888
	ds_read_b128 v[234:237], v145 offset:38912
	ds_read_b128 v[238:241], v145 offset:39936
	global_load_lds_dwordx4 v[248:249], off
	v_lshl_add_u64 v[248:249], s[80:81], 0, v[132:133]
	s_mov_b32 m0, s87
	s_nop 0
	global_load_lds_dwordx4 v[248:249], off
	s_waitcnt vmcnt(8)
	s_waitcnt lgkmcnt(0)
	s_setprio 1
	s_barrier
	v_mfma_f32_16x16x32_bf16 v[124:127], v[178:181], v[210:213], v[124:127]
	v_mfma_f32_16x16x32_bf16 v[124:127], v[182:185], v[214:217], v[124:127]
	v_mfma_f32_16x16x32_bf16 v[116:119], v[178:181], v[218:221], v[116:119]
	v_mfma_f32_16x16x32_bf16 v[116:119], v[182:185], v[222:225], v[116:119]
	v_mfma_f32_16x16x32_bf16 v[108:111], v[178:181], v[226:229], v[108:111]
	v_mfma_f32_16x16x32_bf16 v[108:111], v[182:185], v[230:233], v[108:111]
	v_mfma_f32_16x16x32_bf16 v[100:103], v[178:181], v[234:237], v[100:103]
	v_mfma_f32_16x16x32_bf16 v[100:103], v[182:185], v[238:241], v[100:103]
	v_mfma_f32_16x16x32_bf16 v[96:99], v[186:189], v[234:237], v[96:99]
	v_mfma_f32_16x16x32_bf16 v[96:99], v[190:193], v[238:241], v[96:99]
	v_mfma_f32_16x16x32_bf16 v[104:107], v[186:189], v[226:229], v[104:107]
	v_mfma_f32_16x16x32_bf16 v[104:107], v[190:193], v[230:233], v[104:107]
	v_mfma_f32_16x16x32_bf16 v[112:115], v[186:189], v[218:221], v[112:115]
	v_mfma_f32_16x16x32_bf16 v[112:115], v[190:193], v[222:225], v[112:115]
	v_mfma_f32_16x16x32_bf16 v[120:123], v[186:189], v[210:213], v[120:123]
	v_mfma_f32_16x16x32_bf16 v[120:123], v[190:193], v[214:217], v[120:123]
	v_mfma_f32_16x16x32_bf16 v[68:71], v[194:197], v[210:213], v[68:71]
	v_mfma_f32_16x16x32_bf16 v[68:71], v[198:201], v[214:217], v[68:71]
	v_mfma_f32_16x16x32_bf16 v[52:55], v[194:197], v[218:221], v[52:55]
	v_mfma_f32_16x16x32_bf16 v[52:55], v[198:201], v[222:225], v[52:55]
	v_mfma_f32_16x16x32_bf16 v[44:47], v[194:197], v[226:229], v[44:47]
	v_mfma_f32_16x16x32_bf16 v[44:47], v[198:201], v[230:233], v[44:47]
	v_mfma_f32_16x16x32_bf16 v[36:39], v[194:197], v[234:237], v[36:39]
	v_mfma_f32_16x16x32_bf16 v[36:39], v[198:201], v[238:241], v[36:39]
	v_mfma_f32_16x16x32_bf16 v[32:35], v[202:205], v[234:237], v[32:35]
	v_mfma_f32_16x16x32_bf16 v[32:35], v[206:209], v[238:241], v[32:35]
	v_mfma_f32_16x16x32_bf16 v[40:43], v[202:205], v[226:229], v[40:43]
	v_mfma_f32_16x16x32_bf16 v[40:43], v[206:209], v[230:233], v[40:43]
	s_setprio 2
	s_barrier
; #define PG8_STAGE(bufoff, gbase, voff) do { _Pragma("unroll") for (int _i = 0; _i < 2; ++_i) \
;         __builtin_amdgcn_global_load_lds((const unsigned*)((const char*)(gbase) + (voff)[_i]), (PG8_LAS unsigned*)(lds + (bufoff) + ldsw + _i * 8192), 16, 0, 0); } while (0)
; #define PG8_LDA(dst, b, h) do { _Pragma("unroll") for (int m = 0; m < 4; ++m) _Pragma("unroll") for (int k = 0; k < 2; ++k) dst[m][k] = *(const PG8_LAS bf16x8*)(lds + PG8_SA(b, h) + aoff + m * 2048 + k * 1024); } while (0)
; #define PG8_MMA(ai, bj, At, Bt) do { __builtin_amdgcn_s_setprio(1); _Pragma("unroll") for (int m = 0; m < 4; ++m) _Pragma("unroll") for (int n = 0; n < 2; ++n) _Pragma("unroll") for (int k = 0; k < 2; ++k) \
;         acc[ai][bj][m][n] = __builtin_amdgcn_mfma_f32_16x16x32_bf16(Bt[n][k], At[m][k], acc[ai][bj][m][n], 0, 0, 0); __builtin_amdgcn_s_setprio(0); } while (0)
; #define PG8_WAIT_V(n) asm volatile("s_waitcnt vmcnt(" #n ")" ::: "memory")
; #define PG8_WAIT_L(n) asm volatile("s_waitcnt lgkmcnt(" #n ")" ::: "memory")
; #define PG8_BAR __builtin_amdgcn_s_barrier()
; #define PG8_SCHED __builtin_amdgcn_sched_barrier(0)
; template <class Epi, class Sched, bool ALIGN_EPI = false, bool SP2 = false>
; __device__ __forceinline__ void gemm_phase(PG8_LAS unsigned char* lds, const Gemm g, const Sched& S, const Epi& E) {
;     ...
;             PG8_LDA(At, 1, 1); PG8_STAGE(PG8_SB(1, 0), b3, voffB); PG8_STAGE(PG8_SB(1, 1), b3 + hstep, voffB); PG8_STAGE(PG8_SA(1, 0), a3, voffA);
;             PG8_WAIT_V(8); PG8_WAIT_L(0); PG8_BAR; PG8_MMA(1, 0, At, B0); PG8_MMA(1, 1, At, B1); PG8_BAR; PG8_SCHED;
;     ...
;         if constexpr (ALIGN_EPI) { if (wr == 0) PG8_BAR; }
	v_mfma_f32_16x16x32_bf16 v[48:51], v[202:205], v[218:221], v[48:51]
	v_mfma_f32_16x16x32_bf16 v[48:51], v[206:209], v[222:225], v[48:51]
	v_mfma_f32_16x16x32_bf16 v[64:67], v[202:205], v[210:213], v[64:67]
	v_mfma_f32_16x16x32_bf16 v[64:67], v[206:209], v[214:217], v[64:67]
	s_setprio 0
	s_add_i32 s62, s62, s3
	v_lshl_add_u64 v[166:167], v[166:167], 0, s[8:9]
	s_mov_b32 m0, s62
	ds_read_b128 v[210:213], v145 offset:49152
	ds_read_b128 v[214:217], v145 offset:50176
	ds_read_b128 v[218:221], v145 offset:51200
	ds_read_b128 v[222:225], v145 offset:52224
	ds_read_b128 v[226:229], v145 offset:53248
	ds_read_b128 v[230:233], v145 offset:54272
	ds_read_b128 v[234:237], v145 offset:55296
	ds_read_b128 v[238:241], v145 offset:56320
	global_load_lds_dwordx4 v[166:167], off
	s_add_i32 m0, s62, 0x2000
	s_add_u32 s78, s78, 0x80080
	v_lshl_add_u64 v[166:167], v[242:243], 0, s[8:9]
	s_addc_u32 s79, s79, 0
	s_add_i32 s62, s63, s3
	global_load_lds_dwordx4 v[166:167], off
	v_lshl_add_u64 v[166:167], s[78:79], 0, v[130:131]
	s_mov_b32 m0, s62
	s_nop 0
	global_load_lds_dwordx4 v[166:167], off
	v_lshl_add_u64 v[166:167], s[78:79], 0, v[134:135]
	s_add_i32 m0, s62, 0x2000
	s_nop 0
	global_load_lds_dwordx4 v[166:167], off
	v_lshl_add_u64 v[166:167], v[244:245], 0, s[8:9]
	s_mov_b32 m0, s89
	s_nop 0
	global_load_lds_dwordx4 v[166:167], off
	v_lshl_add_u64 v[166:167], v[246:247], 0, s[8:9]
	s_mov_b32 m0, s90
	s_nop 0
	global_load_lds_dwordx4 v[166:167], off
	s_waitcnt vmcnt(8)
	s_waitcnt lgkmcnt(0)
	s_setprio 1
	s_barrier
	v_mfma_f32_16x16x32_bf16 v[92:95], v[178:181], v[210:213], v[92:95]
	v_mfma_f32_16x16x32_bf16 v[92:95], v[182:185], v[214:217], v[92:95]
	v_mfma_f32_16x16x32_bf16 v[84:87], v[178:181], v[218:221], v[84:87]
	v_mfma_f32_16x16x32_bf16 v[84:87], v[182:185], v[222:225], v[84:87]
	v_mfma_f32_16x16x32_bf16 v[76:79], v[178:181], v[226:229], v[76:79]
	v_mfma_f32_16x16x32_bf16 v[76:79], v[182:185], v[230:233], v[76:79]
	v_mfma_f32_16x16x32_bf16 v[60:63], v[178:181], v[234:237], v[60:63]
	v_mfma_f32_16x16x32_bf16 v[60:63], v[182:185], v[238:241], v[60:63]
	v_mfma_f32_16x16x32_bf16 v[56:59], v[186:189], v[234:237], v[56:59]
	v_mfma_f32_16x16x32_bf16 v[56:59], v[190:193], v[238:241], v[56:59]
	v_mfma_f32_16x16x32_bf16 v[72:75], v[186:189], v[226:229], v[72:75]
	v_mfma_f32_16x16x32_bf16 v[72:75], v[190:193], v[230:233], v[72:75]
	v_mfma_f32_16x16x32_bf16 v[80:83], v[186:189], v[218:221], v[80:83]
	v_mfma_f32_16x16x32_bf16 v[80:83], v[190:193], v[222:225], v[80:83]
	v_mfma_f32_16x16x32_bf16 v[88:91], v[186:189], v[210:213], v[88:91]
	v_mfma_f32_16x16x32_bf16 v[88:91], v[190:193], v[214:217], v[88:91]
	v_mfma_f32_16x16x32_bf16 v[28:31], v[194:197], v[210:213], v[28:31]
	v_mfma_f32_16x16x32_bf16 v[28:31], v[198:201], v[214:217], v[28:31]
	v_mfma_f32_16x16x32_bf16 v[20:23], v[194:197], v[218:221], v[20:23]
	v_mfma_f32_16x16x32_bf16 v[20:23], v[198:201], v[222:225], v[20:23]
	v_mfma_f32_16x16x32_bf16 v[12:15], v[194:197], v[226:229], v[12:15]
	v_mfma_f32_16x16x32_bf16 v[12:15], v[198:201], v[230:233], v[12:15]
	v_mfma_f32_16x16x32_bf16 v[4:7], v[194:197], v[234:237], v[4:7]
	v_mfma_f32_16x16x32_bf16 v[4:7], v[198:201], v[238:241], v[4:7]
	v_mfma_f32_16x16x32_bf16 v[0:3], v[202:205], v[234:237], v[0:3]
	v_mfma_f32_16x16x32_bf16 v[0:3], v[206:209], v[238:241], v[0:3]
	v_mfma_f32_16x16x32_bf16 v[8:11], v[202:205], v[226:229], v[8:11]
	v_mfma_f32_16x16x32_bf16 v[8:11], v[206:209], v[230:233], v[8:11]
	s_setprio 2
	s_barrier
	v_mfma_f32_16x16x32_bf16 v[16:19], v[202:205], v[218:221], v[16:19]
	v_mfma_f32_16x16x32_bf16 v[16:19], v[206:209], v[222:225], v[16:19]
	v_mfma_f32_16x16x32_bf16 v[24:27], v[202:205], v[210:213], v[24:27]
	v_mfma_f32_16x16x32_bf16 v[24:27], v[206:209], v[214:217], v[24:27]
	s_setprio 0
	s_add_i32 s75, s75, 2
	s_add_u32 s76, s76, 0x100
	s_addc_u32 s77, s77, 0
	s_add_u32 s57, s57, 0x100
	s_addc_u32 s67, s67, 0
	s_cmp_gt_u32 s75, 29
	s_cbranch_scc0 .LBB0_326
	s_and_b64 vcc, exec, s[20:21]
	s_cbranch_vccz .LBB0_329
	s_barrier

; #define PG8_STAGE(bufoff, gbase, voff) do { _Pragma("unroll") for (int _i = 0; _i < 2; ++_i) \
;         __builtin_amdgcn_global_load_lds((const unsigned*)((const char*)(gbase) + (voff)[_i]), (PG8_LAS unsigned*)(lds + (bufoff) + ldsw + _i * 8192), 16, 0, 0); } while (0)
; #define PG8_LDA(dst, b, h) do { _Pragma("unroll") for (int m = 0; m < 4; ++m) _Pragma("unroll") for (int k = 0; k < 2; ++k) dst[m][k] = *(const PG8_LAS bf16x8*)(lds + PG8_SA(b, h) + aoff + m * 2048 + k * 1024); } while (0)
; #define PG8_LDB(dst, b, h) do { _Pragma("unroll") for (int n = 0; n < 2; ++n) _Pragma("unroll") for (int k = 0; k < 2; ++k) dst[n][k] = *(const PG8_LAS bf16x8*)(lds + PG8_SB(b, h) + boff + n * 2048 + k * 1024); } while (0)
; #define PG8_MMA(ai, bj, At, Bt) do { __builtin_amdgcn_s_setprio(1); _Pragma("unroll") for (int m = 0; m < 4; ++m) _Pragma("unroll") for (int n = 0; n < 2; ++n) _Pragma("unroll") for (int k = 0; k < 2; ++k) \
;         acc[ai][bj][m][n] = __builtin_amdgcn_mfma_f32_16x16x32_bf16(Bt[n][k], At[m][k], acc[ai][bj][m][n], 0, 0, 0); __builtin_amdgcn_s_setprio(0); } while (0)
; #define PG8_WAIT_V(n) asm volatile("s_waitcnt vmcnt(" #n ")" ::: "memory")
; #define PG8_WAIT_L(n) asm volatile("s_waitcnt lgkmcnt(" #n ")" ::: "memory")
; #define PG8_BAR __builtin_amdgcn_s_barrier()
; #define PG8_SCHED __builtin_amdgcn_sched_barrier(0)
; template <class Epi, class Sched, bool ALIGN_EPI = false, bool SP2 = false>
; __device__ __forceinline__ void gemm_phase(PG8_LAS unsigned char* lds, const Gemm g, const Sched& S, const Epi& E) {
;     ...
;             PG8_LDB(B0, 0, 0); PG8_LDB(B1, 0, 1); PG8_SCHED; PG8_LDA(At, 0, 0); PG8_STAGE(PG8_SA(1, 1), a1 + hstep, voffA);
;             PG8_WAIT_V(8); PG8_WAIT_L(0); PG8_BAR; PG8_MMA(0, 0, At, B0); PG8_MMA(0, 1, At, B1); PG8_BAR; PG8_SCHED;
;             PG8_LDA(At, 0, 1); PG8_STAGE(PG8_SB(0, 0), b2, voffB); PG8_STAGE(PG8_SB(0, 1), b2 + hstep, voffB); PG8_STAGE(PG8_SA(0, 0), a2, voffA);
;             PG8_WAIT_V(8); PG8_WAIT_L(0); PG8_BAR; PG8_MMA(1, 0, At, B0); PG8_MMA(1, 1, At, B1); PG8_BAR; PG8_SCHED;
.LBB0_557:
	ds_read_b128 v[144:147], v155
	ds_read_b128 v[160:163], v155 offset:1024
	ds_read_b128 v[164:167], v155 offset:2048
	ds_read_b128 v[168:171], v155 offset:3072
	ds_read_b128 v[172:175], v156
	ds_read_b128 v[176:179], v156 offset:1024
	ds_read_b128 v[180:183], v156 offset:2048
	ds_read_b128 v[184:187], v156 offset:3072
	s_add_u32 s54, s50, 0xfff80080
	s_addc_u32 s55, s51, -1
	s_cmp_eq_u32 s73, 28
	s_cselect_b32 s57, s10, s55
	s_cselect_b32 s56, s11, s54
	s_cselect_b32 s55, s41, s72
	s_cselect_b32 s54, s43, s49
	v_lshl_add_u64 v[220:221], s[50:51], 0, v[136:137]
	s_add_i32 m0, s33, 0xc000
	ds_read_b128 v[188:191], v157
	ds_read_b128 v[192:195], v157 offset:1024
	ds_read_b128 v[196:199], v157 offset:2048
	ds_read_b128 v[200:203], v157 offset:3072
	ds_read_b128 v[204:207], v157 offset:4096
	ds_read_b128 v[208:211], v157 offset:5120
	ds_read_b128 v[212:215], v157 offset:6144
	ds_read_b128 v[216:219], v157 offset:7168
	global_load_lds_dwordx4 v[220:221], off
	v_lshl_add_u64 v[220:221], s[50:51], 0, v[138:139]
	s_add_i32 m0, s33, 0xe000
	s_nop 0
	global_load_lds_dwordx4 v[220:221], off
	s_waitcnt vmcnt(8)
	s_waitcnt lgkmcnt(0)
	s_setprio 1
	s_barrier
	v_mfma_f32_16x16x32_bf16 v[124:127], v[144:147], v[188:191], v[124:127]
	v_mfma_f32_16x16x32_bf16 v[124:127], v[160:163], v[192:195], v[124:127]
	v_mfma_f32_16x16x32_bf16 v[108:111], v[144:147], v[196:199], v[108:111]
	v_mfma_f32_16x16x32_bf16 v[108:111], v[160:163], v[200:203], v[108:111]
	v_mfma_f32_16x16x32_bf16 v[92:95], v[144:147], v[204:207], v[92:95]
	v_mfma_f32_16x16x32_bf16 v[92:95], v[160:163], v[208:211], v[92:95]
	v_mfma_f32_16x16x32_bf16 v[76:79], v[144:147], v[212:215], v[76:79]
	v_mfma_f32_16x16x32_bf16 v[76:79], v[160:163], v[216:219], v[76:79]
	v_mfma_f32_16x16x32_bf16 v[72:75], v[164:167], v[212:215], v[72:75]
	v_mfma_f32_16x16x32_bf16 v[72:75], v[168:171], v[216:219], v[72:75]
	v_mfma_f32_16x16x32_bf16 v[88:91], v[164:167], v[204:207], v[88:91]
	v_mfma_f32_16x16x32_bf16 v[88:91], v[168:171], v[208:211], v[88:91]
	v_mfma_f32_16x16x32_bf16 v[104:107], v[164:167], v[196:199], v[104:107]
	v_mfma_f32_16x16x32_bf16 v[104:107], v[168:171], v[200:203], v[104:107]
	v_mfma_f32_16x16x32_bf16 v[120:123], v[164:167], v[188:191], v[120:123]
	v_mfma_f32_16x16x32_bf16 v[120:123], v[168:171], v[192:195], v[120:123]
	v_mfma_f32_16x16x32_bf16 v[116:119], v[172:175], v[188:191], v[116:119]
	v_mfma_f32_16x16x32_bf16 v[116:119], v[176:179], v[192:195], v[116:119]
	v_mfma_f32_16x16x32_bf16 v[100:103], v[172:175], v[196:199], v[100:103]
	v_mfma_f32_16x16x32_bf16 v[100:103], v[176:179], v[200:203], v[100:103]
	v_mfma_f32_16x16x32_bf16 v[84:87], v[172:175], v[204:207], v[84:87]
	v_mfma_f32_16x16x32_bf16 v[84:87], v[176:179], v[208:211], v[84:87]
	v_mfma_f32_16x16x32_bf16 v[68:71], v[172:175], v[212:215], v[68:71]
	v_mfma_f32_16x16x32_bf16 v[68:71], v[176:179], v[216:219], v[68:71]
	v_mfma_f32_16x16x32_bf16 v[64:67], v[180:183], v[212:215], v[64:67]
	v_mfma_f32_16x16x32_bf16 v[64:67], v[184:187], v[216:219], v[64:67]
	v_mfma_f32_16x16x32_bf16 v[80:83], v[180:183], v[204:207], v[80:83]
	v_mfma_f32_16x16x32_bf16 v[80:83], v[184:187], v[208:211], v[80:83]
	s_setprio 2
	s_barrier
	v_mfma_f32_16x16x32_bf16 v[96:99], v[180:183], v[196:199], v[96:99]
	v_mfma_f32_16x16x32_bf16 v[96:99], v[184:187], v[200:203], v[96:99]
	v_mfma_f32_16x16x32_bf16 v[112:115], v[180:183], v[188:191], v[112:115]
	v_mfma_f32_16x16x32_bf16 v[112:115], v[184:187], v[192:195], v[112:115]
	s_setprio 0
	s_add_i32 s62, s67, s3
	v_lshl_add_u64 v[220:221], s[54:55], 0, v[130:131]
	s_mov_b32 m0, s62
	ds_read_b128 v[188:191], v157 offset:16384
	ds_read_b128 v[192:195], v157 offset:17408
	ds_read_b128 v[196:199], v157 offset:18432
	ds_read_b128 v[200:203], v157 offset:19456
	ds_read_b128 v[204:207], v157 offset:20480
	ds_read_b128 v[208:211], v157 offset:21504
	ds_read_b128 v[212:215], v157 offset:22528
	ds_read_b128 v[216:219], v157 offset:23552
	global_load_lds_dwordx4 v[220:221], off
	s_add_i32 m0, s62, 0x2000
	s_add_u32 s62, s54, 0x80000
	v_lshl_add_u64 v[222:223], s[54:55], 0, v[134:135]
	s_addc_u32 s63, s55, 0
	s_add_i32 s74, s70, s3
	global_load_lds_dwordx4 v[222:223], off
	v_lshl_add_u64 v[224:225], s[62:63], 0, v[130:131]
	s_mov_b32 m0, s74
	v_lshl_add_u64 v[226:227], s[56:57], 0, v[132:133]
	global_load_lds_dwordx4 v[224:225], off
	v_lshl_add_u64 v[224:225], s[62:63], 0, v[134:135]
	s_add_i32 m0, s74, 0x2000
	s_nop 0
	global_load_lds_dwordx4 v[224:225], off
	v_lshl_add_u64 v[224:225], s[56:57], 0, v[128:129]
	s_mov_b32 m0, s33
	s_nop 0
	global_load_lds_dwordx4 v[224:225], off
	s_mov_b32 m0, s35
	s_nop 0
	global_load_lds_dwordx4 v[226:227], off
	s_waitcnt vmcnt(8)
	s_waitcnt lgkmcnt(0)
	s_setprio 1
	s_barrier
; #define PG8_STAGE(bufoff, gbase, voff) do { _Pragma("unroll") for (int _i = 0; _i < 2; ++_i) \
;         __builtin_amdgcn_global_load_lds((const unsigned*)((const char*)(gbase) + (voff)[_i]), (PG8_LAS unsigned*)(lds + (bufoff) + ldsw + _i * 8192), 16, 0, 0); } while (0)
; #define PG8_LDA(dst, b, h) do { _Pragma("unroll") for (int m = 0; m < 4; ++m) _Pragma("unroll") for (int k = 0; k < 2; ++k) dst[m][k] = *(const PG8_LAS bf16x8*)(lds + PG8_SA(b, h) + aoff + m * 2048 + k * 1024); } while (0)
; #define PG8_LDB(dst, b, h) do { _Pragma("unroll") for (int n = 0; n < 2; ++n) _Pragma("unroll") for (int k = 0; k < 2; ++k) dst[n][k] = *(const PG8_LAS bf16x8*)(lds + PG8_SB(b, h) + boff + n * 2048 + k * 1024); } while (0)
; #define PG8_MMA(ai, bj, At, Bt) do { __builtin_amdgcn_s_setprio(1); _Pragma("unroll") for (int m = 0; m < 4; ++m) _Pragma("unroll") for (int n = 0; n < 2; ++n) _Pragma("unroll") for (int k = 0; k < 2; ++k) \
;         acc[ai][bj][m][n] = __builtin_amdgcn_mfma_f32_16x16x32_bf16(Bt[n][k], At[m][k], acc[ai][bj][m][n], 0, 0, 0); __builtin_amdgcn_s_setprio(0); } while (0)
; #define PG8_WAIT_V(n) asm volatile("s_waitcnt vmcnt(" #n ")" ::: "memory")
; #define PG8_WAIT_L(n) asm volatile("s_waitcnt lgkmcnt(" #n ")" ::: "memory")
; #define PG8_BAR __builtin_amdgcn_s_barrier()
; #define PG8_SCHED __builtin_amdgcn_sched_barrier(0)
; template <class Epi, class Sched, bool ALIGN_EPI = false, bool SP2 = false>
; __device__ __forceinline__ void gemm_phase(PG8_LAS unsigned char* lds, const Gemm g, const Sched& S, const Epi& E) {
;     ...
;             PG8_WAIT_V(8); PG8_WAIT_L(0); PG8_BAR; PG8_MMA(1, 0, At, B0); PG8_MMA(1, 1, At, B1); PG8_BAR; PG8_SCHED;
;             PG8_LDB(B0, 1, 0); PG8_LDB(B1, 1, 1); PG8_SCHED; PG8_LDA(At, 1, 0); PG8_STAGE(PG8_SA(0, 1), a2 + hstep, voffA);
;             PG8_WAIT_V(8); PG8_WAIT_L(0); PG8_BAR; PG8_MMA(0, 0, At, B0); PG8_MMA(0, 1, At, B1); PG8_BAR; PG8_SCHED;
	v_mfma_f32_16x16x32_bf16 v[60:63], v[144:147], v[188:191], v[60:63]
	v_mfma_f32_16x16x32_bf16 v[60:63], v[160:163], v[192:195], v[60:63]
	v_mfma_f32_16x16x32_bf16 v[44:47], v[144:147], v[196:199], v[44:47]
	v_mfma_f32_16x16x32_bf16 v[44:47], v[160:163], v[200:203], v[44:47]
	v_mfma_f32_16x16x32_bf16 v[28:31], v[144:147], v[204:207], v[28:31]
	v_mfma_f32_16x16x32_bf16 v[28:31], v[160:163], v[208:211], v[28:31]
	v_mfma_f32_16x16x32_bf16 v[12:15], v[144:147], v[212:215], v[12:15]
	v_mfma_f32_16x16x32_bf16 v[12:15], v[160:163], v[216:219], v[12:15]
	v_mfma_f32_16x16x32_bf16 v[8:11], v[164:167], v[212:215], v[8:11]
	v_mfma_f32_16x16x32_bf16 v[8:11], v[168:171], v[216:219], v[8:11]
	v_mfma_f32_16x16x32_bf16 v[24:27], v[164:167], v[204:207], v[24:27]
	v_mfma_f32_16x16x32_bf16 v[24:27], v[168:171], v[208:211], v[24:27]
	v_mfma_f32_16x16x32_bf16 v[40:43], v[164:167], v[196:199], v[40:43]
	v_mfma_f32_16x16x32_bf16 v[40:43], v[168:171], v[200:203], v[40:43]
	v_mfma_f32_16x16x32_bf16 v[56:59], v[164:167], v[188:191], v[56:59]
	v_mfma_f32_16x16x32_bf16 v[56:59], v[168:171], v[192:195], v[56:59]
	v_mfma_f32_16x16x32_bf16 v[52:55], v[172:175], v[188:191], v[52:55]
	v_mfma_f32_16x16x32_bf16 v[52:55], v[176:179], v[192:195], v[52:55]
	v_mfma_f32_16x16x32_bf16 v[36:39], v[172:175], v[196:199], v[36:39]
	v_mfma_f32_16x16x32_bf16 v[36:39], v[176:179], v[200:203], v[36:39]
	v_mfma_f32_16x16x32_bf16 v[20:23], v[172:175], v[204:207], v[20:23]
	v_mfma_f32_16x16x32_bf16 v[20:23], v[176:179], v[208:211], v[20:23]
	v_mfma_f32_16x16x32_bf16 v[4:7], v[172:175], v[212:215], v[4:7]
	v_mfma_f32_16x16x32_bf16 v[4:7], v[176:179], v[216:219], v[4:7]
	v_mfma_f32_16x16x32_bf16 v[0:3], v[180:183], v[212:215], v[0:3]
	v_mfma_f32_16x16x32_bf16 v[0:3], v[184:187], v[216:219], v[0:3]
	v_mfma_f32_16x16x32_bf16 v[16:19], v[180:183], v[204:207], v[16:19]
	v_mfma_f32_16x16x32_bf16 v[16:19], v[184:187], v[208:211], v[16:19]
	s_setprio 2
	s_barrier
	v_mfma_f32_16x16x32_bf16 v[32:35], v[180:183], v[196:199], v[32:35]
	v_mfma_f32_16x16x32_bf16 v[32:35], v[184:187], v[200:203], v[32:35]
	v_mfma_f32_16x16x32_bf16 v[48:51], v[180:183], v[188:191], v[48:51]
	v_mfma_f32_16x16x32_bf16 v[48:51], v[184:187], v[192:195], v[48:51]
	s_setprio 0
	s_add_i32 s62, 0, 0x18000
	v_add_u32_e32 v159, s62, v153
	s_add_i32 s63, 0, 0x1c000
	ds_read_b128 v[144:147], v159
	ds_read_b128 v[160:163], v159 offset:1024
	ds_read_b128 v[164:167], v159 offset:2048
	ds_read_b128 v[168:171], v159 offset:3072
	v_add_u32_e32 v159, s63, v153
	ds_read_b128 v[172:175], v159
	ds_read_b128 v[176:179], v159 offset:1024
	ds_read_b128 v[180:183], v159 offset:2048
	ds_read_b128 v[184:187], v159 offset:3072
	s_add_u32 s56, s56, 0x80000
	s_addc_u32 s57, s57, 0
	s_mov_b32 m0, s52
	v_lshl_add_u64 v[228:229], s[56:57], 0, v[128:129]
	ds_read_b128 v[188:191], v157 offset:32768
	ds_read_b128 v[192:195], v157 offset:33792
	ds_read_b128 v[196:199], v157 offset:34816
	ds_read_b128 v[200:203], v157 offset:35840
	ds_read_b128 v[204:207], v157 offset:36864
	ds_read_b128 v[208:211], v157 offset:37888
	ds_read_b128 v[212:215], v157 offset:38912
	ds_read_b128 v[216:219], v157 offset:39936
	global_load_lds_dwordx4 v[228:229], off
	v_lshl_add_u64 v[228:229], s[56:57], 0, v[132:133]
	s_mov_b32 m0, s53
	s_nop 0
	global_load_lds_dwordx4 v[228:229], off
	s_waitcnt vmcnt(8)
	s_waitcnt lgkmcnt(0)
	s_setprio 1
	s_barrier
	v_mfma_f32_16x16x32_bf16 v[124:127], v[144:147], v[188:191], v[124:127]
	v_mfma_f32_16x16x32_bf16 v[124:127], v[160:163], v[192:195], v[124:127]
	v_mfma_f32_16x16x32_bf16 v[108:111], v[144:147], v[196:199], v[108:111]
	v_mfma_f32_16x16x32_bf16 v[108:111], v[160:163], v[200:203], v[108:111]
	v_mfma_f32_16x16x32_bf16 v[92:95], v[144:147], v[204:207], v[92:95]
	v_mfma_f32_16x16x32_bf16 v[92:95], v[160:163], v[208:211], v[92:95]
	v_mfma_f32_16x16x32_bf16 v[76:79], v[144:147], v[212:215], v[76:79]
	v_mfma_f32_16x16x32_bf16 v[76:79], v[160:163], v[216:219], v[76:79]
	v_mfma_f32_16x16x32_bf16 v[72:75], v[164:167], v[212:215], v[72:75]
	v_mfma_f32_16x16x32_bf16 v[72:75], v[168:171], v[216:219], v[72:75]
	v_mfma_f32_16x16x32_bf16 v[88:91], v[164:167], v[204:207], v[88:91]
	v_mfma_f32_16x16x32_bf16 v[88:91], v[168:171], v[208:211], v[88:91]
	v_mfma_f32_16x16x32_bf16 v[104:107], v[164:167], v[196:199], v[104:107]
	v_mfma_f32_16x16x32_bf16 v[104:107], v[168:171], v[200:203], v[104:107]
	v_mfma_f32_16x16x32_bf16 v[120:123], v[164:167], v[188:191], v[120:123]
	v_mfma_f32_16x16x32_bf16 v[120:123], v[168:171], v[192:195], v[120:123]
	v_mfma_f32_16x16x32_bf16 v[116:119], v[172:175], v[188:191], v[116:119]
	v_mfma_f32_16x16x32_bf16 v[116:119], v[176:179], v[192:195], v[116:119]
	v_mfma_f32_16x16x32_bf16 v[100:103], v[172:175], v[196:199], v[100:103]
	v_mfma_f32_16x16x32_bf16 v[100:103], v[176:179], v[200:203], v[100:103]
	v_mfma_f32_16x16x32_bf16 v[84:87], v[172:175], v[204:207], v[84:87]
	v_mfma_f32_16x16x32_bf16 v[84:87], v[176:179], v[208:211], v[84:87]
	v_mfma_f32_16x16x32_bf16 v[68:71], v[172:175], v[212:215], v[68:71]
	v_mfma_f32_16x16x32_bf16 v[68:71], v[176:179], v[216:219], v[68:71]
	v_mfma_f32_16x16x32_bf16 v[64:67], v[180:183], v[212:215], v[64:67]
	v_mfma_f32_16x16x32_bf16 v[64:67], v[184:187], v[216:219], v[64:67]
	v_mfma_f32_16x16x32_bf16 v[80:83], v[180:183], v[204:207], v[80:83]
	v_mfma_f32_16x16x32_bf16 v[80:83], v[184:187], v[208:211], v[80:83]
	s_setprio 2
	s_barrier
; #define PG8_STAGE(bufoff, gbase, voff) do { _Pragma("unroll") for (int _i = 0; _i < 2; ++_i) \
;         __builtin_amdgcn_global_load_lds((const unsigned*)((const char*)(gbase) + (voff)[_i]), (PG8_LAS unsigned*)(lds + (bufoff) + ldsw + _i * 8192), 16, 0, 0); } while (0)
; #define PG8_LDA(dst, b, h) do { _Pragma("unroll") for (int m = 0; m < 4; ++m) _Pragma("unroll") for (int k = 0; k < 2; ++k) dst[m][k] = *(const PG8_LAS bf16x8*)(lds + PG8_SA(b, h) + aoff + m * 2048 + k * 1024); } while (0)
; #define PG8_MMA(ai, bj, At, Bt) do { __builtin_amdgcn_s_setprio(1); _Pragma("unroll") for (int m = 0; m < 4; ++m) _Pragma("unroll") for (int n = 0; n < 2; ++n) _Pragma("unroll") for (int k = 0; k < 2; ++k) \
;         acc[ai][bj][m][n] = __builtin_amdgcn_mfma_f32_16x16x32_bf16(Bt[n][k], At[m][k], acc[ai][bj][m][n], 0, 0, 0); __builtin_amdgcn_s_setprio(0); } while (0)
; #define PG8_WAIT_V(n) asm volatile("s_waitcnt vmcnt(" #n ")" ::: "memory")
; #define PG8_WAIT_L(n) asm volatile("s_waitcnt lgkmcnt(" #n ")" ::: "memory")
; #define PG8_BAR __builtin_amdgcn_s_barrier()
; #define PG8_SCHED __builtin_amdgcn_sched_barrier(0)
; template <class Epi, class Sched, bool ALIGN_EPI = false, bool SP2 = false>
; __device__ __forceinline__ void gemm_phase(PG8_LAS unsigned char* lds, const Gemm g, const Sched& S, const Epi& E) {
;     ...
;             PG8_LDA(At, 1, 1); PG8_STAGE(PG8_SB(1, 0), b3, voffB); PG8_STAGE(PG8_SB(1, 1), b3 + hstep, voffB); PG8_STAGE(PG8_SA(1, 0), a3, voffA);
;             PG8_WAIT_V(8); PG8_WAIT_L(0); PG8_BAR; PG8_MMA(1, 0, At, B0); PG8_MMA(1, 1, At, B1); PG8_BAR; PG8_SCHED;
;     ...
;         if constexpr (ALIGN_EPI) { if (wr == 0) PG8_BAR; }
	v_mfma_f32_16x16x32_bf16 v[96:99], v[180:183], v[196:199], v[96:99]
	v_mfma_f32_16x16x32_bf16 v[96:99], v[184:187], v[200:203], v[96:99]
	v_mfma_f32_16x16x32_bf16 v[112:115], v[180:183], v[188:191], v[112:115]
	v_mfma_f32_16x16x32_bf16 v[112:115], v[184:187], v[192:195], v[112:115]
	s_setprio 0
	s_add_i32 s56, s62, s3
	v_lshl_add_u64 v[220:221], v[220:221], 0, s[20:21]
	s_mov_b32 m0, s56
	ds_read_b128 v[188:191], v157 offset:49152
	ds_read_b128 v[192:195], v157 offset:50176
	ds_read_b128 v[196:199], v157 offset:51200
	ds_read_b128 v[200:203], v157 offset:52224
	ds_read_b128 v[204:207], v157 offset:53248
	ds_read_b128 v[208:211], v157 offset:54272
	ds_read_b128 v[212:215], v157 offset:55296
	ds_read_b128 v[216:219], v157 offset:56320
	global_load_lds_dwordx4 v[220:221], off
	s_add_i32 m0, s56, 0x2000
	s_add_u32 s54, s54, 0x80080
	v_lshl_add_u64 v[220:221], v[222:223], 0, s[20:21]
	s_addc_u32 s55, s55, 0
	s_add_i32 s56, s63, s3
	global_load_lds_dwordx4 v[220:221], off
	v_lshl_add_u64 v[220:221], s[54:55], 0, v[130:131]
	s_mov_b32 m0, s56
	s_nop 0
	global_load_lds_dwordx4 v[220:221], off
	v_lshl_add_u64 v[220:221], s[54:55], 0, v[134:135]
	s_add_i32 m0, s56, 0x2000
	s_nop 0
	global_load_lds_dwordx4 v[220:221], off
	v_lshl_add_u64 v[220:221], v[224:225], 0, s[20:21]
	s_mov_b32 m0, s64
	s_nop 0
	global_load_lds_dwordx4 v[220:221], off
	v_lshl_add_u64 v[220:221], v[226:227], 0, s[20:21]
	s_mov_b32 m0, s65
	s_nop 0
	global_load_lds_dwordx4 v[220:221], off
	s_waitcnt vmcnt(8)
	s_waitcnt lgkmcnt(0)
	s_setprio 1
	s_barrier
	v_mfma_f32_16x16x32_bf16 v[60:63], v[144:147], v[188:191], v[60:63]
	v_mfma_f32_16x16x32_bf16 v[60:63], v[160:163], v[192:195], v[60:63]
	v_mfma_f32_16x16x32_bf16 v[44:47], v[144:147], v[196:199], v[44:47]
	v_mfma_f32_16x16x32_bf16 v[44:47], v[160:163], v[200:203], v[44:47]
	v_mfma_f32_16x16x32_bf16 v[28:31], v[144:147], v[204:207], v[28:31]
	v_mfma_f32_16x16x32_bf16 v[28:31], v[160:163], v[208:211], v[28:31]
	v_mfma_f32_16x16x32_bf16 v[12:15], v[144:147], v[212:215], v[12:15]
	v_mfma_f32_16x16x32_bf16 v[12:15], v[160:163], v[216:219], v[12:15]
	v_mfma_f32_16x16x32_bf16 v[8:11], v[164:167], v[212:215], v[8:11]
	v_mfma_f32_16x16x32_bf16 v[8:11], v[168:171], v[216:219], v[8:11]
	v_mfma_f32_16x16x32_bf16 v[24:27], v[164:167], v[204:207], v[24:27]
	v_mfma_f32_16x16x32_bf16 v[24:27], v[168:171], v[208:211], v[24:27]
	v_mfma_f32_16x16x32_bf16 v[40:43], v[164:167], v[196:199], v[40:43]
	v_mfma_f32_16x16x32_bf16 v[40:43], v[168:171], v[200:203], v[40:43]
	v_mfma_f32_16x16x32_bf16 v[56:59], v[164:167], v[188:191], v[56:59]
	v_mfma_f32_16x16x32_bf16 v[56:59], v[168:171], v[192:195], v[56:59]
	v_mfma_f32_16x16x32_bf16 v[52:55], v[172:175], v[188:191], v[52:55]
	v_mfma_f32_16x16x32_bf16 v[52:55], v[176:179], v[192:195], v[52:55]
	v_mfma_f32_16x16x32_bf16 v[36:39], v[172:175], v[196:199], v[36:39]
	v_mfma_f32_16x16x32_bf16 v[36:39], v[176:179], v[200:203], v[36:39]
	v_mfma_f32_16x16x32_bf16 v[20:23], v[172:175], v[204:207], v[20:23]
	v_mfma_f32_16x16x32_bf16 v[20:23], v[176:179], v[208:211], v[20:23]
	v_mfma_f32_16x16x32_bf16 v[4:7], v[172:175], v[212:215], v[4:7]
	v_mfma_f32_16x16x32_bf16 v[4:7], v[176:179], v[216:219], v[4:7]
	v_mfma_f32_16x16x32_bf16 v[0:3], v[180:183], v[212:215], v[0:3]
	v_mfma_f32_16x16x32_bf16 v[0:3], v[184:187], v[216:219], v[0:3]
	v_mfma_f32_16x16x32_bf16 v[16:19], v[180:183], v[204:207], v[16:19]
	v_mfma_f32_16x16x32_bf16 v[16:19], v[184:187], v[208:211], v[16:19]
	s_setprio 2
	s_barrier
	v_mfma_f32_16x16x32_bf16 v[32:35], v[180:183], v[196:199], v[32:35]
	v_mfma_f32_16x16x32_bf16 v[32:35], v[184:187], v[200:203], v[32:35]
	v_mfma_f32_16x16x32_bf16 v[48:51], v[180:183], v[188:191], v[48:51]
	v_mfma_f32_16x16x32_bf16 v[48:51], v[184:187], v[192:195], v[48:51]
	s_setprio 0
	s_add_i32 s73, s73, 2
	s_add_u32 s50, s50, 0x100
	s_addc_u32 s51, s51, 0
	s_add_u32 s49, s49, 0x100
	s_addc_u32 s72, s72, 0
	s_cmp_gt_u32 s73, 29
	s_cbranch_scc0 .LBB0_557
	s_and_b64 vcc, exec, s[38:39]
	s_cbranch_vccz .LBB0_560
	s_barrier

; #define PG8_STAGE(bufoff, gbase, voff) do { _Pragma("unroll") for (int _i = 0; _i < 2; ++_i) \
;         __builtin_amdgcn_global_load_lds((const unsigned*)((const char*)(gbase) + (voff)[_i]), (PG8_LAS unsigned*)(lds + (bufoff) + ldsw + _i * 8192), 16, 0, 0); } while (0)
; #define PG8_LDA(dst, b, h) do { _Pragma("unroll") for (int m = 0; m < 4; ++m) _Pragma("unroll") for (int k = 0; k < 2; ++k) dst[m][k] = *(const PG8_LAS bf16x8*)(lds + PG8_SA(b, h) + aoff + m * 2048 + k * 1024); } while (0)
; #define PG8_LDB(dst, b, h) do { _Pragma("unroll") for (int n = 0; n < 2; ++n) _Pragma("unroll") for (int k = 0; k < 2; ++k) dst[n][k] = *(const PG8_LAS bf16x8*)(lds + PG8_SB(b, h) + boff + n * 2048 + k * 1024); } while (0)
; #define PG8_MMA(ai, bj, At, Bt) do { __builtin_amdgcn_s_setprio(1); _Pragma("unroll") for (int m = 0; m < 4; ++m) _Pragma("unroll") for (int n = 0; n < 2; ++n) _Pragma("unroll") for (int k = 0; k < 2; ++k) \
;         acc[ai][bj][m][n] = __builtin_amdgcn_mfma_f32_16x16x32_bf16(Bt[n][k], At[m][k], acc[ai][bj][m][n], 0, 0, 0); __builtin_amdgcn_s_setprio(0); } while (0)
; #define PG8_WAIT_V(n) asm volatile("s_waitcnt vmcnt(" #n ")" ::: "memory")
; #define PG8_WAIT_L(n) asm volatile("s_waitcnt lgkmcnt(" #n ")" ::: "memory")
; #define PG8_BAR __builtin_amdgcn_s_barrier()
; #define PG8_SCHED __builtin_amdgcn_sched_barrier(0)
; template <class Epi, class Sched, bool ALIGN_EPI = false, bool SP2 = false>
; __device__ __forceinline__ void gemm_phase(PG8_LAS unsigned char* lds, const Gemm g, const Sched& S, const Epi& E) {
;     ...
;             PG8_LDB(B0, 0, 0); PG8_LDB(B1, 0, 1); PG8_SCHED; PG8_LDA(At, 0, 0); PG8_STAGE(PG8_SA(1, 1), a1 + hstep, voffA);
;             PG8_WAIT_V(8); PG8_WAIT_L(0); PG8_BAR; PG8_MMA(0, 0, At, B0); PG8_MMA(0, 1, At, B1); PG8_BAR; PG8_SCHED;
;             PG8_LDA(At, 0, 1); PG8_STAGE(PG8_SB(0, 0), b2, voffB); PG8_STAGE(PG8_SB(0, 1), b2 + hstep, voffB); PG8_STAGE(PG8_SA(0, 0), a2, voffA);
;             PG8_WAIT_V(8); PG8_WAIT_L(0); PG8_BAR; PG8_MMA(1, 0, At, B0); PG8_MMA(1, 1, At, B1); PG8_BAR; PG8_SCHED;
.LBB0_700:
	ds_read_b128 v[164:167], v155
	ds_read_b128 v[168:171], v155 offset:1024
	ds_read_b128 v[172:175], v155 offset:2048
	ds_read_b128 v[176:179], v155 offset:3072
	ds_read_b128 v[180:183], v157
	ds_read_b128 v[184:187], v157 offset:1024
	ds_read_b128 v[188:191], v157 offset:2048
	ds_read_b128 v[192:195], v157 offset:3072
	s_add_u32 s46, s44, 0xfff80080
	s_addc_u32 s47, s45, -1
	s_cmp_eq_u32 s67, 28
	s_cselect_b32 s49, s10, s47
	s_cselect_b32 s48, s11, s46
	s_cselect_b32 s47, s21, s66
	s_cselect_b32 s46, s37, s65
	v_lshl_add_u64 v[228:229], s[44:45], 0, v[138:139]
	s_add_i32 m0, s43, 0xc000
	ds_read_b128 v[196:199], v159
	ds_read_b128 v[200:203], v159 offset:1024
	ds_read_b128 v[204:207], v159 offset:2048
	ds_read_b128 v[208:211], v159 offset:3072
	ds_read_b128 v[212:215], v159 offset:4096
	ds_read_b128 v[216:219], v159 offset:5120
	ds_read_b128 v[220:223], v159 offset:6144
	ds_read_b128 v[224:227], v159 offset:7168
	global_load_lds_dwordx4 v[228:229], off
	v_lshl_add_u64 v[228:229], s[44:45], 0, v[140:141]
	s_add_i32 m0, s43, 0xe000
	s_nop 0
	global_load_lds_dwordx4 v[228:229], off
	s_waitcnt vmcnt(8)
	s_waitcnt lgkmcnt(0)
	s_setprio 1
	s_barrier
	v_mfma_f32_16x16x32_bf16 v[124:127], v[164:167], v[196:199], v[124:127]
	v_mfma_f32_16x16x32_bf16 v[124:127], v[168:171], v[200:203], v[124:127]
	v_mfma_f32_16x16x32_bf16 v[108:111], v[164:167], v[204:207], v[108:111]
	v_mfma_f32_16x16x32_bf16 v[108:111], v[168:171], v[208:211], v[108:111]
	v_mfma_f32_16x16x32_bf16 v[92:95], v[164:167], v[212:215], v[92:95]
	v_mfma_f32_16x16x32_bf16 v[92:95], v[168:171], v[216:219], v[92:95]
	v_mfma_f32_16x16x32_bf16 v[76:79], v[164:167], v[220:223], v[76:79]
	v_mfma_f32_16x16x32_bf16 v[76:79], v[168:171], v[224:227], v[76:79]
	v_mfma_f32_16x16x32_bf16 v[72:75], v[172:175], v[220:223], v[72:75]
	v_mfma_f32_16x16x32_bf16 v[72:75], v[176:179], v[224:227], v[72:75]
	v_mfma_f32_16x16x32_bf16 v[88:91], v[172:175], v[212:215], v[88:91]
	v_mfma_f32_16x16x32_bf16 v[88:91], v[176:179], v[216:219], v[88:91]
	v_mfma_f32_16x16x32_bf16 v[104:107], v[172:175], v[204:207], v[104:107]
	v_mfma_f32_16x16x32_bf16 v[104:107], v[176:179], v[208:211], v[104:107]
	v_mfma_f32_16x16x32_bf16 v[120:123], v[172:175], v[196:199], v[120:123]
	v_mfma_f32_16x16x32_bf16 v[120:123], v[176:179], v[200:203], v[120:123]
	v_mfma_f32_16x16x32_bf16 v[116:119], v[180:183], v[196:199], v[116:119]
	v_mfma_f32_16x16x32_bf16 v[116:119], v[184:187], v[200:203], v[116:119]
	v_mfma_f32_16x16x32_bf16 v[100:103], v[180:183], v[204:207], v[100:103]
	v_mfma_f32_16x16x32_bf16 v[100:103], v[184:187], v[208:211], v[100:103]
	v_mfma_f32_16x16x32_bf16 v[84:87], v[180:183], v[212:215], v[84:87]
	v_mfma_f32_16x16x32_bf16 v[84:87], v[184:187], v[216:219], v[84:87]
	v_mfma_f32_16x16x32_bf16 v[68:71], v[180:183], v[220:223], v[68:71]
	v_mfma_f32_16x16x32_bf16 v[68:71], v[184:187], v[224:227], v[68:71]
	v_mfma_f32_16x16x32_bf16 v[64:67], v[188:191], v[220:223], v[64:67]
	v_mfma_f32_16x16x32_bf16 v[64:67], v[192:195], v[224:227], v[64:67]
	v_mfma_f32_16x16x32_bf16 v[80:83], v[188:191], v[212:215], v[80:83]
	v_mfma_f32_16x16x32_bf16 v[80:83], v[192:195], v[216:219], v[80:83]
	s_setprio 2
	s_barrier
	v_mfma_f32_16x16x32_bf16 v[96:99], v[188:191], v[204:207], v[96:99]
	v_mfma_f32_16x16x32_bf16 v[96:99], v[192:195], v[208:211], v[96:99]
	v_mfma_f32_16x16x32_bf16 v[112:115], v[188:191], v[196:199], v[112:115]
	v_mfma_f32_16x16x32_bf16 v[112:115], v[192:195], v[200:203], v[112:115]
	s_setprio 0
	s_add_i32 s62, s58, s3
	v_lshl_add_u64 v[228:229], s[46:47], 0, v[130:131]
	s_mov_b32 m0, s62
	ds_read_b128 v[196:199], v159 offset:16384
	ds_read_b128 v[200:203], v159 offset:17408
	ds_read_b128 v[204:207], v159 offset:18432
	ds_read_b128 v[208:211], v159 offset:19456
	ds_read_b128 v[212:215], v159 offset:20480
	ds_read_b128 v[216:219], v159 offset:21504
	ds_read_b128 v[220:223], v159 offset:22528
	ds_read_b128 v[224:227], v159 offset:23552
	global_load_lds_dwordx4 v[228:229], off
	s_add_i32 m0, s62, 0x2000
	s_add_u32 s62, s46, 0x80000
	v_lshl_add_u64 v[230:231], s[46:47], 0, v[134:135]
	s_addc_u32 s63, s47, 0
	s_add_i32 s68, s59, s3
	global_load_lds_dwordx4 v[230:231], off
	v_lshl_add_u64 v[232:233], s[62:63], 0, v[130:131]
	s_mov_b32 m0, s68
	v_lshl_add_u64 v[234:235], s[48:49], 0, v[132:133]
	global_load_lds_dwordx4 v[232:233], off
	v_lshl_add_u64 v[232:233], s[62:63], 0, v[134:135]
	s_add_i32 m0, s68, 0x2000
	s_nop 0
	global_load_lds_dwordx4 v[232:233], off
	v_lshl_add_u64 v[232:233], s[48:49], 0, v[128:129]
	s_mov_b32 m0, s43
	s_nop 0
	global_load_lds_dwordx4 v[232:233], off
	s_mov_b32 m0, s50
	s_nop 0
	global_load_lds_dwordx4 v[234:235], off
	s_waitcnt vmcnt(8)
	s_waitcnt lgkmcnt(0)
	s_setprio 1
	s_barrier
; #define PG8_STAGE(bufoff, gbase, voff) do { _Pragma("unroll") for (int _i = 0; _i < 2; ++_i) \
;         __builtin_amdgcn_global_load_lds((const unsigned*)((const char*)(gbase) + (voff)[_i]), (PG8_LAS unsigned*)(lds + (bufoff) + ldsw + _i * 8192), 16, 0, 0); } while (0)
; #define PG8_LDA(dst, b, h) do { _Pragma("unroll") for (int m = 0; m < 4; ++m) _Pragma("unroll") for (int k = 0; k < 2; ++k) dst[m][k] = *(const PG8_LAS bf16x8*)(lds + PG8_SA(b, h) + aoff + m * 2048 + k * 1024); } while (0)
; #define PG8_LDB(dst, b, h) do { _Pragma("unroll") for (int n = 0; n < 2; ++n) _Pragma("unroll") for (int k = 0; k < 2; ++k) dst[n][k] = *(const PG8_LAS bf16x8*)(lds + PG8_SB(b, h) + boff + n * 2048 + k * 1024); } while (0)
; #define PG8_MMA(ai, bj, At, Bt) do { __builtin_amdgcn_s_setprio(1); _Pragma("unroll") for (int m = 0; m < 4; ++m) _Pragma("unroll") for (int n = 0; n < 2; ++n) _Pragma("unroll") for (int k = 0; k < 2; ++k) \
;         acc[ai][bj][m][n] = __builtin_amdgcn_mfma_f32_16x16x32_bf16(Bt[n][k], At[m][k], acc[ai][bj][m][n], 0, 0, 0); __builtin_amdgcn_s_setprio(0); } while (0)
; #define PG8_WAIT_V(n) asm volatile("s_waitcnt vmcnt(" #n ")" ::: "memory")
; #define PG8_WAIT_L(n) asm volatile("s_waitcnt lgkmcnt(" #n ")" ::: "memory")
; #define PG8_BAR __builtin_amdgcn_s_barrier()
; #define PG8_SCHED __builtin_amdgcn_sched_barrier(0)
; template <class Epi, class Sched, bool ALIGN_EPI = false, bool SP2 = false>
; __device__ __forceinline__ void gemm_phase(PG8_LAS unsigned char* lds, const Gemm g, const Sched& S, const Epi& E) {
;     ...
;             PG8_WAIT_V(8); PG8_WAIT_L(0); PG8_BAR; PG8_MMA(1, 0, At, B0); PG8_MMA(1, 1, At, B1); PG8_BAR; PG8_SCHED;
;             PG8_LDB(B0, 1, 0); PG8_LDB(B1, 1, 1); PG8_SCHED; PG8_LDA(At, 1, 0); PG8_STAGE(PG8_SA(0, 1), a2 + hstep, voffA);
;             PG8_WAIT_V(8); PG8_WAIT_L(0); PG8_BAR; PG8_MMA(0, 0, At, B0); PG8_MMA(0, 1, At, B1); PG8_BAR; PG8_SCHED;
	v_mfma_f32_16x16x32_bf16 v[60:63], v[164:167], v[196:199], v[60:63]
	v_mfma_f32_16x16x32_bf16 v[60:63], v[168:171], v[200:203], v[60:63]
	v_mfma_f32_16x16x32_bf16 v[44:47], v[164:167], v[204:207], v[44:47]
	v_mfma_f32_16x16x32_bf16 v[44:47], v[168:171], v[208:211], v[44:47]
	v_mfma_f32_16x16x32_bf16 v[28:31], v[164:167], v[212:215], v[28:31]
	v_mfma_f32_16x16x32_bf16 v[28:31], v[168:171], v[216:219], v[28:31]
	v_mfma_f32_16x16x32_bf16 v[12:15], v[164:167], v[220:223], v[12:15]
	v_mfma_f32_16x16x32_bf16 v[12:15], v[168:171], v[224:227], v[12:15]
	v_mfma_f32_16x16x32_bf16 v[8:11], v[172:175], v[220:223], v[8:11]
	v_mfma_f32_16x16x32_bf16 v[8:11], v[176:179], v[224:227], v[8:11]
	v_mfma_f32_16x16x32_bf16 v[24:27], v[172:175], v[212:215], v[24:27]
	v_mfma_f32_16x16x32_bf16 v[24:27], v[176:179], v[216:219], v[24:27]
	v_mfma_f32_16x16x32_bf16 v[40:43], v[172:175], v[204:207], v[40:43]
	v_mfma_f32_16x16x32_bf16 v[40:43], v[176:179], v[208:211], v[40:43]
	v_mfma_f32_16x16x32_bf16 v[56:59], v[172:175], v[196:199], v[56:59]
	v_mfma_f32_16x16x32_bf16 v[56:59], v[176:179], v[200:203], v[56:59]
	v_mfma_f32_16x16x32_bf16 v[52:55], v[180:183], v[196:199], v[52:55]
	v_mfma_f32_16x16x32_bf16 v[52:55], v[184:187], v[200:203], v[52:55]
	v_mfma_f32_16x16x32_bf16 v[36:39], v[180:183], v[204:207], v[36:39]
	v_mfma_f32_16x16x32_bf16 v[36:39], v[184:187], v[208:211], v[36:39]
	v_mfma_f32_16x16x32_bf16 v[20:23], v[180:183], v[212:215], v[20:23]
	v_mfma_f32_16x16x32_bf16 v[20:23], v[184:187], v[216:219], v[20:23]
	v_mfma_f32_16x16x32_bf16 v[4:7], v[180:183], v[220:223], v[4:7]
	v_mfma_f32_16x16x32_bf16 v[4:7], v[184:187], v[224:227], v[4:7]
	v_mfma_f32_16x16x32_bf16 v[0:3], v[188:191], v[220:223], v[0:3]
	v_mfma_f32_16x16x32_bf16 v[0:3], v[192:195], v[224:227], v[0:3]
	v_mfma_f32_16x16x32_bf16 v[16:19], v[188:191], v[212:215], v[16:19]
	v_mfma_f32_16x16x32_bf16 v[16:19], v[192:195], v[216:219], v[16:19]
	s_setprio 2
	s_barrier
	v_mfma_f32_16x16x32_bf16 v[32:35], v[188:191], v[204:207], v[32:35]
	v_mfma_f32_16x16x32_bf16 v[32:35], v[192:195], v[208:211], v[32:35]
	v_mfma_f32_16x16x32_bf16 v[48:51], v[188:191], v[196:199], v[48:51]
	v_mfma_f32_16x16x32_bf16 v[48:51], v[192:195], v[200:203], v[48:51]
	s_setprio 0
	s_add_i32 s62, 0, 0x18000
	v_add_u32_e32 v161, s62, v147
	s_add_i32 s63, 0, 0x1c000
	ds_read_b128 v[164:167], v161
	ds_read_b128 v[168:171], v161 offset:1024
	ds_read_b128 v[172:175], v161 offset:2048
	ds_read_b128 v[176:179], v161 offset:3072
	v_add_u32_e32 v161, s63, v147
	ds_read_b128 v[180:183], v161
	ds_read_b128 v[184:187], v161 offset:1024
	ds_read_b128 v[188:191], v161 offset:2048
	ds_read_b128 v[192:195], v161 offset:3072
	s_add_u32 s48, s48, 0x80000
	s_addc_u32 s49, s49, 0
	s_mov_b32 m0, s51
	v_lshl_add_u64 v[236:237], s[48:49], 0, v[128:129]
	ds_read_b128 v[196:199], v159 offset:32768
	ds_read_b128 v[200:203], v159 offset:33792
	ds_read_b128 v[204:207], v159 offset:34816
	ds_read_b128 v[208:211], v159 offset:35840
	ds_read_b128 v[212:215], v159 offset:36864
	ds_read_b128 v[216:219], v159 offset:37888
	ds_read_b128 v[220:223], v159 offset:38912
	ds_read_b128 v[224:227], v159 offset:39936
	global_load_lds_dwordx4 v[236:237], off
	v_lshl_add_u64 v[236:237], s[48:49], 0, v[132:133]
	s_mov_b32 m0, s52
	s_nop 0
	global_load_lds_dwordx4 v[236:237], off
	s_waitcnt vmcnt(8)
	s_waitcnt lgkmcnt(0)
	s_setprio 1
	s_barrier
	v_mfma_f32_16x16x32_bf16 v[124:127], v[164:167], v[196:199], v[124:127]
	v_mfma_f32_16x16x32_bf16 v[124:127], v[168:171], v[200:203], v[124:127]
	v_mfma_f32_16x16x32_bf16 v[108:111], v[164:167], v[204:207], v[108:111]
	v_mfma_f32_16x16x32_bf16 v[108:111], v[168:171], v[208:211], v[108:111]
	v_mfma_f32_16x16x32_bf16 v[92:95], v[164:167], v[212:215], v[92:95]
	v_mfma_f32_16x16x32_bf16 v[92:95], v[168:171], v[216:219], v[92:95]
	v_mfma_f32_16x16x32_bf16 v[76:79], v[164:167], v[220:223], v[76:79]
	v_mfma_f32_16x16x32_bf16 v[76:79], v[168:171], v[224:227], v[76:79]
	v_mfma_f32_16x16x32_bf16 v[72:75], v[172:175], v[220:223], v[72:75]
	v_mfma_f32_16x16x32_bf16 v[72:75], v[176:179], v[224:227], v[72:75]
	v_mfma_f32_16x16x32_bf16 v[88:91], v[172:175], v[212:215], v[88:91]
	v_mfma_f32_16x16x32_bf16 v[88:91], v[176:179], v[216:219], v[88:91]
	v_mfma_f32_16x16x32_bf16 v[104:107], v[172:175], v[204:207], v[104:107]
	v_mfma_f32_16x16x32_bf16 v[104:107], v[176:179], v[208:211], v[104:107]
	v_mfma_f32_16x16x32_bf16 v[120:123], v[172:175], v[196:199], v[120:123]
	v_mfma_f32_16x16x32_bf16 v[120:123], v[176:179], v[200:203], v[120:123]
	v_mfma_f32_16x16x32_bf16 v[116:119], v[180:183], v[196:199], v[116:119]
	v_mfma_f32_16x16x32_bf16 v[116:119], v[184:187], v[200:203], v[116:119]
	v_mfma_f32_16x16x32_bf16 v[100:103], v[180:183], v[204:207], v[100:103]
	v_mfma_f32_16x16x32_bf16 v[100:103], v[184:187], v[208:211], v[100:103]
	v_mfma_f32_16x16x32_bf16 v[84:87], v[180:183], v[212:215], v[84:87]
	v_mfma_f32_16x16x32_bf16 v[84:87], v[184:187], v[216:219], v[84:87]
	v_mfma_f32_16x16x32_bf16 v[68:71], v[180:183], v[220:223], v[68:71]
	v_mfma_f32_16x16x32_bf16 v[68:71], v[184:187], v[224:227], v[68:71]
	v_mfma_f32_16x16x32_bf16 v[64:67], v[188:191], v[220:223], v[64:67]
	v_mfma_f32_16x16x32_bf16 v[64:67], v[192:195], v[224:227], v[64:67]
	v_mfma_f32_16x16x32_bf16 v[80:83], v[188:191], v[212:215], v[80:83]
	v_mfma_f32_16x16x32_bf16 v[80:83], v[192:195], v[216:219], v[80:83]
	s_setprio 2
	s_barrier
; #define PG8_STAGE(bufoff, gbase, voff) do { _Pragma("unroll") for (int _i = 0; _i < 2; ++_i) \
;         __builtin_amdgcn_global_load_lds((const unsigned*)((const char*)(gbase) + (voff)[_i]), (PG8_LAS unsigned*)(lds + (bufoff) + ldsw + _i * 8192), 16, 0, 0); } while (0)
; #define PG8_LDA(dst, b, h) do { _Pragma("unroll") for (int m = 0; m < 4; ++m) _Pragma("unroll") for (int k = 0; k < 2; ++k) dst[m][k] = *(const PG8_LAS bf16x8*)(lds + PG8_SA(b, h) + aoff + m * 2048 + k * 1024); } while (0)
; #define PG8_MMA(ai, bj, At, Bt) do { __builtin_amdgcn_s_setprio(1); _Pragma("unroll") for (int m = 0; m < 4; ++m) _Pragma("unroll") for (int n = 0; n < 2; ++n) _Pragma("unroll") for (int k = 0; k < 2; ++k) \
;         acc[ai][bj][m][n] = __builtin_amdgcn_mfma_f32_16x16x32_bf16(Bt[n][k], At[m][k], acc[ai][bj][m][n], 0, 0, 0); __builtin_amdgcn_s_setprio(0); } while (0)
; #define PG8_WAIT_V(n) asm volatile("s_waitcnt vmcnt(" #n ")" ::: "memory")
; #define PG8_WAIT_L(n) asm volatile("s_waitcnt lgkmcnt(" #n ")" ::: "memory")
; #define PG8_BAR __builtin_amdgcn_s_barrier()
; #define PG8_SCHED __builtin_amdgcn_sched_barrier(0)
; template <class Epi, class Sched, bool ALIGN_EPI = false, bool SP2 = false>
; __device__ __forceinline__ void gemm_phase(PG8_LAS unsigned char* lds, const Gemm g, const Sched& S, const Epi& E) {
;     ...
;             PG8_LDA(At, 1, 1); PG8_STAGE(PG8_SB(1, 0), b3, voffB); PG8_STAGE(PG8_SB(1, 1), b3 + hstep, voffB); PG8_STAGE(PG8_SA(1, 0), a3, voffA);
;             PG8_WAIT_V(8); PG8_WAIT_L(0); PG8_BAR; PG8_MMA(1, 0, At, B0); PG8_MMA(1, 1, At, B1); PG8_BAR; PG8_SCHED;
;     ...
;         if constexpr (ALIGN_EPI) { if (wr == 0) PG8_BAR; }
	v_mfma_f32_16x16x32_bf16 v[96:99], v[188:191], v[204:207], v[96:99]
	v_mfma_f32_16x16x32_bf16 v[96:99], v[192:195], v[208:211], v[96:99]
	v_mfma_f32_16x16x32_bf16 v[112:115], v[188:191], v[196:199], v[112:115]
	v_mfma_f32_16x16x32_bf16 v[112:115], v[192:195], v[200:203], v[112:115]
	s_setprio 0
	s_add_i32 s48, s62, s3
	v_lshl_add_u64 v[228:229], v[228:229], 0, s[8:9]
	s_mov_b32 m0, s48
	ds_read_b128 v[196:199], v159 offset:49152
	ds_read_b128 v[200:203], v159 offset:50176
	ds_read_b128 v[204:207], v159 offset:51200
	ds_read_b128 v[208:211], v159 offset:52224
	ds_read_b128 v[212:215], v159 offset:53248
	ds_read_b128 v[216:219], v159 offset:54272
	ds_read_b128 v[220:223], v159 offset:55296
	ds_read_b128 v[224:227], v159 offset:56320
	global_load_lds_dwordx4 v[228:229], off
	s_add_i32 m0, s48, 0x2000
	s_add_u32 s46, s46, 0x80080
	v_lshl_add_u64 v[228:229], v[230:231], 0, s[8:9]
	s_addc_u32 s47, s47, 0
	s_add_i32 s48, s63, s3
	global_load_lds_dwordx4 v[228:229], off
	v_lshl_add_u64 v[228:229], s[46:47], 0, v[130:131]
	s_mov_b32 m0, s48
	s_nop 0
	global_load_lds_dwordx4 v[228:229], off
	v_lshl_add_u64 v[228:229], s[46:47], 0, v[134:135]
	s_add_i32 m0, s48, 0x2000
	s_nop 0
	global_load_lds_dwordx4 v[228:229], off
	v_lshl_add_u64 v[228:229], v[232:233], 0, s[8:9]
	s_mov_b32 m0, s55
	s_nop 0
	global_load_lds_dwordx4 v[228:229], off
	v_lshl_add_u64 v[228:229], v[234:235], 0, s[8:9]
	s_mov_b32 m0, s56
	s_nop 0
	global_load_lds_dwordx4 v[228:229], off
	s_waitcnt vmcnt(8)
	s_waitcnt lgkmcnt(0)
	s_setprio 1
	s_barrier
	v_mfma_f32_16x16x32_bf16 v[60:63], v[164:167], v[196:199], v[60:63]
	v_mfma_f32_16x16x32_bf16 v[60:63], v[168:171], v[200:203], v[60:63]
	v_mfma_f32_16x16x32_bf16 v[44:47], v[164:167], v[204:207], v[44:47]
	v_mfma_f32_16x16x32_bf16 v[44:47], v[168:171], v[208:211], v[44:47]
	v_mfma_f32_16x16x32_bf16 v[28:31], v[164:167], v[212:215], v[28:31]
	v_mfma_f32_16x16x32_bf16 v[28:31], v[168:171], v[216:219], v[28:31]
	v_mfma_f32_16x16x32_bf16 v[12:15], v[164:167], v[220:223], v[12:15]
	v_mfma_f32_16x16x32_bf16 v[12:15], v[168:171], v[224:227], v[12:15]
	v_mfma_f32_16x16x32_bf16 v[8:11], v[172:175], v[220:223], v[8:11]
	v_mfma_f32_16x16x32_bf16 v[8:11], v[176:179], v[224:227], v[8:11]
	v_mfma_f32_16x16x32_bf16 v[24:27], v[172:175], v[212:215], v[24:27]
	v_mfma_f32_16x16x32_bf16 v[24:27], v[176:179], v[216:219], v[24:27]
	v_mfma_f32_16x16x32_bf16 v[40:43], v[172:175], v[204:207], v[40:43]
	v_mfma_f32_16x16x32_bf16 v[40:43], v[176:179], v[208:211], v[40:43]
	v_mfma_f32_16x16x32_bf16 v[56:59], v[172:175], v[196:199], v[56:59]
	v_mfma_f32_16x16x32_bf16 v[56:59], v[176:179], v[200:203], v[56:59]
	v_mfma_f32_16x16x32_bf16 v[52:55], v[180:183], v[196:199], v[52:55]
	v_mfma_f32_16x16x32_bf16 v[52:55], v[184:187], v[200:203], v[52:55]
	v_mfma_f32_16x16x32_bf16 v[36:39], v[180:183], v[204:207], v[36:39]
	v_mfma_f32_16x16x32_bf16 v[36:39], v[184:187], v[208:211], v[36:39]
	v_mfma_f32_16x16x32_bf16 v[20:23], v[180:183], v[212:215], v[20:23]
	v_mfma_f32_16x16x32_bf16 v[20:23], v[184:187], v[216:219], v[20:23]
	v_mfma_f32_16x16x32_bf16 v[4:7], v[180:183], v[220:223], v[4:7]
	v_mfma_f32_16x16x32_bf16 v[4:7], v[184:187], v[224:227], v[4:7]
	v_mfma_f32_16x16x32_bf16 v[0:3], v[188:191], v[220:223], v[0:3]
	v_mfma_f32_16x16x32_bf16 v[0:3], v[192:195], v[224:227], v[0:3]
	v_mfma_f32_16x16x32_bf16 v[16:19], v[188:191], v[212:215], v[16:19]
	v_mfma_f32_16x16x32_bf16 v[16:19], v[192:195], v[216:219], v[16:19]
	s_setprio 2
	s_barrier
	v_mfma_f32_16x16x32_bf16 v[32:35], v[188:191], v[204:207], v[32:35]
	v_mfma_f32_16x16x32_bf16 v[32:35], v[192:195], v[208:211], v[32:35]
	v_mfma_f32_16x16x32_bf16 v[48:51], v[188:191], v[196:199], v[48:51]
	v_mfma_f32_16x16x32_bf16 v[48:51], v[192:195], v[200:203], v[48:51]
	s_setprio 0
	s_add_i32 s67, s67, 2
	s_add_u32 s44, s44, 0x100
	s_addc_u32 s45, s45, 0
	s_add_u32 s65, s65, 0x100
	s_addc_u32 s66, s66, 0
	s_cmp_gt_u32 s67, 29
	s_cbranch_scc0 .LBB0_700
	s_and_b64 vcc, exec, s[12:13]
	s_cbranch_vccz .LBB0_703
	s_barrier

; #define PG8_STAGE(bufoff, gbase, voff) do { _Pragma("unroll") for (int _i = 0; _i < 2; ++_i) \
;         __builtin_amdgcn_global_load_lds((const unsigned*)((const char*)(gbase) + (voff)[_i]), (PG8_LAS unsigned*)(lds + (bufoff) + ldsw + _i * 8192), 16, 0, 0); } while (0)
; #define PG8_LDA(dst, b, h) do { _Pragma("unroll") for (int m = 0; m < 4; ++m) _Pragma("unroll") for (int k = 0; k < 2; ++k) dst[m][k] = *(const PG8_LAS bf16x8*)(lds + PG8_SA(b, h) + aoff + m * 2048 + k * 1024); } while (0)
; #define PG8_LDB(dst, b, h) do { _Pragma("unroll") for (int n = 0; n < 2; ++n) _Pragma("unroll") for (int k = 0; k < 2; ++k) dst[n][k] = *(const PG8_LAS bf16x8*)(lds + PG8_SB(b, h) + boff + n * 2048 + k * 1024); } while (0)
; #define PG8_MMA(ai, bj, At, Bt) do { __builtin_amdgcn_s_setprio(1); _Pragma("unroll") for (int m = 0; m < 4; ++m) _Pragma("unroll") for (int n = 0; n < 2; ++n) _Pragma("unroll") for (int k = 0; k < 2; ++k) \
;         acc[ai][bj][m][n] = __builtin_amdgcn_mfma_f32_16x16x32_bf16(Bt[n][k], At[m][k], acc[ai][bj][m][n], 0, 0, 0); __builtin_amdgcn_s_setprio(0); } while (0)
; #define PG8_WAIT_V(n) asm volatile("s_waitcnt vmcnt(" #n ")" ::: "memory")
; #define PG8_WAIT_L(n) asm volatile("s_waitcnt lgkmcnt(" #n ")" ::: "memory")
; #define PG8_BAR __builtin_amdgcn_s_barrier()
; #define PG8_SCHED __builtin_amdgcn_sched_barrier(0)
; template <class Epi, class Sched, bool ALIGN_EPI = false, bool SP2 = false>
; __device__ __forceinline__ void gemm_phase(PG8_LAS unsigned char* lds, const Gemm g, const Sched& S, const Epi& E) {
;     ...
;             PG8_LDB(B0, 0, 0); PG8_LDB(B1, 0, 1); PG8_SCHED; PG8_LDA(At, 0, 0); PG8_STAGE(PG8_SA(1, 1), a1 + hstep, voffA);
;             PG8_WAIT_V(8); PG8_WAIT_L(0); PG8_BAR; PG8_MMA(0, 0, At, B0); PG8_MMA(0, 1, At, B1); PG8_BAR; PG8_SCHED;
;             PG8_LDA(At, 0, 1); PG8_STAGE(PG8_SB(0, 0), b2, voffB); PG8_STAGE(PG8_SB(0, 1), b2 + hstep, voffB); PG8_STAGE(PG8_SA(0, 0), a2, voffA);
;             PG8_WAIT_V(8); PG8_WAIT_L(0); PG8_BAR; PG8_MMA(1, 0, At, B0); PG8_MMA(1, 1, At, B1); PG8_BAR; PG8_SCHED;
.LBB0_779:
	ds_read_b128 v[144:147], v155
	ds_read_b128 v[160:163], v155 offset:1024
	ds_read_b128 v[164:167], v155 offset:2048
	ds_read_b128 v[168:171], v155 offset:3072
	ds_read_b128 v[172:175], v156
	ds_read_b128 v[176:179], v156 offset:1024
	ds_read_b128 v[180:183], v156 offset:2048
	ds_read_b128 v[184:187], v156 offset:3072
	s_add_u32 s40, s38, 0xffea0080
	s_addc_u32 s41, s39, -1
	s_cmpk_eq_i32 s58, 0x54
	s_cselect_b32 s43, s7, s41
	s_cselect_b32 s42, s6, s40
	s_cselect_b32 s41, s37, s57
	s_cselect_b32 s40, s36, s11
	v_lshl_add_u64 v[220:221], s[38:39], 0, v[136:137]
	s_add_i32 m0, s33, 0xc000
	ds_read_b128 v[188:191], v157
	ds_read_b128 v[192:195], v157 offset:1024
	ds_read_b128 v[196:199], v157 offset:2048
	ds_read_b128 v[200:203], v157 offset:3072
	ds_read_b128 v[204:207], v157 offset:4096
	ds_read_b128 v[208:211], v157 offset:5120
	ds_read_b128 v[212:215], v157 offset:6144
	ds_read_b128 v[216:219], v157 offset:7168
	global_load_lds_dwordx4 v[220:221], off
	v_lshl_add_u64 v[220:221], s[38:39], 0, v[138:139]
	s_add_i32 m0, s33, 0xe000
	s_nop 0
	global_load_lds_dwordx4 v[220:221], off
	s_waitcnt vmcnt(8)
	s_waitcnt lgkmcnt(0)
	s_setprio 1
	s_barrier
	v_mfma_f32_16x16x32_bf16 v[124:127], v[144:147], v[188:191], v[124:127]
	v_mfma_f32_16x16x32_bf16 v[124:127], v[160:163], v[192:195], v[124:127]
	v_mfma_f32_16x16x32_bf16 v[108:111], v[144:147], v[196:199], v[108:111]
	v_mfma_f32_16x16x32_bf16 v[108:111], v[160:163], v[200:203], v[108:111]
	v_mfma_f32_16x16x32_bf16 v[92:95], v[144:147], v[204:207], v[92:95]
	v_mfma_f32_16x16x32_bf16 v[92:95], v[160:163], v[208:211], v[92:95]
	v_mfma_f32_16x16x32_bf16 v[76:79], v[144:147], v[212:215], v[76:79]
	v_mfma_f32_16x16x32_bf16 v[76:79], v[160:163], v[216:219], v[76:79]
	v_mfma_f32_16x16x32_bf16 v[72:75], v[164:167], v[212:215], v[72:75]
	v_mfma_f32_16x16x32_bf16 v[72:75], v[168:171], v[216:219], v[72:75]
	v_mfma_f32_16x16x32_bf16 v[88:91], v[164:167], v[204:207], v[88:91]
	v_mfma_f32_16x16x32_bf16 v[88:91], v[168:171], v[208:211], v[88:91]
	v_mfma_f32_16x16x32_bf16 v[104:107], v[164:167], v[196:199], v[104:107]
	v_mfma_f32_16x16x32_bf16 v[104:107], v[168:171], v[200:203], v[104:107]
	v_mfma_f32_16x16x32_bf16 v[120:123], v[164:167], v[188:191], v[120:123]
	v_mfma_f32_16x16x32_bf16 v[120:123], v[168:171], v[192:195], v[120:123]
	v_mfma_f32_16x16x32_bf16 v[116:119], v[172:175], v[188:191], v[116:119]
	v_mfma_f32_16x16x32_bf16 v[116:119], v[176:179], v[192:195], v[116:119]
	v_mfma_f32_16x16x32_bf16 v[100:103], v[172:175], v[196:199], v[100:103]
	v_mfma_f32_16x16x32_bf16 v[100:103], v[176:179], v[200:203], v[100:103]
	v_mfma_f32_16x16x32_bf16 v[84:87], v[172:175], v[204:207], v[84:87]
	v_mfma_f32_16x16x32_bf16 v[84:87], v[176:179], v[208:211], v[84:87]
	v_mfma_f32_16x16x32_bf16 v[68:71], v[172:175], v[212:215], v[68:71]
	v_mfma_f32_16x16x32_bf16 v[68:71], v[176:179], v[216:219], v[68:71]
	v_mfma_f32_16x16x32_bf16 v[64:67], v[180:183], v[212:215], v[64:67]
	v_mfma_f32_16x16x32_bf16 v[64:67], v[184:187], v[216:219], v[64:67]
	v_mfma_f32_16x16x32_bf16 v[80:83], v[180:183], v[204:207], v[80:83]
	v_mfma_f32_16x16x32_bf16 v[80:83], v[184:187], v[208:211], v[80:83]
	s_setprio 2
	s_barrier
	v_mfma_f32_16x16x32_bf16 v[96:99], v[180:183], v[196:199], v[96:99]
	v_mfma_f32_16x16x32_bf16 v[96:99], v[184:187], v[200:203], v[96:99]
	v_mfma_f32_16x16x32_bf16 v[112:115], v[180:183], v[188:191], v[112:115]
	v_mfma_f32_16x16x32_bf16 v[112:115], v[184:187], v[192:195], v[112:115]
	s_setprio 0
	s_add_i32 s59, s52, s3
	v_lshl_add_u64 v[220:221], s[40:41], 0, v[130:131]
	s_mov_b32 m0, s59
	ds_read_b128 v[188:191], v157 offset:16384
	ds_read_b128 v[192:195], v157 offset:17408
	ds_read_b128 v[196:199], v157 offset:18432
	ds_read_b128 v[200:203], v157 offset:19456
	ds_read_b128 v[204:207], v157 offset:20480
	ds_read_b128 v[208:211], v157 offset:21504
	ds_read_b128 v[212:215], v157 offset:22528
	ds_read_b128 v[216:219], v157 offset:23552
	global_load_lds_dwordx4 v[220:221], off
	s_add_i32 m0, s59, 0x2000
	s_add_u32 s62, s40, 0x160000
	v_lshl_add_u64 v[222:223], s[40:41], 0, v[134:135]
	s_addc_u32 s63, s41, 0
	s_add_i32 s59, s53, s3
	global_load_lds_dwordx4 v[222:223], off
	v_lshl_add_u64 v[224:225], s[62:63], 0, v[130:131]
	s_mov_b32 m0, s59
	v_lshl_add_u64 v[226:227], s[42:43], 0, v[132:133]
	global_load_lds_dwordx4 v[224:225], off
	v_lshl_add_u64 v[224:225], s[62:63], 0, v[134:135]
	s_add_i32 m0, s59, 0x2000
	s_nop 0
	global_load_lds_dwordx4 v[224:225], off
	v_lshl_add_u64 v[224:225], s[42:43], 0, v[128:129]
	s_mov_b32 m0, s33
	s_nop 0
	global_load_lds_dwordx4 v[224:225], off
	s_mov_b32 m0, s35
	s_nop 0
	global_load_lds_dwordx4 v[226:227], off
	s_waitcnt vmcnt(8)
	s_waitcnt lgkmcnt(0)
	s_setprio 1
	s_barrier
; #define PG8_STAGE(bufoff, gbase, voff) do { _Pragma("unroll") for (int _i = 0; _i < 2; ++_i) \
;         __builtin_amdgcn_global_load_lds((const unsigned*)((const char*)(gbase) + (voff)[_i]), (PG8_LAS unsigned*)(lds + (bufoff) + ldsw + _i * 8192), 16, 0, 0); } while (0)
; #define PG8_LDA(dst, b, h) do { _Pragma("unroll") for (int m = 0; m < 4; ++m) _Pragma("unroll") for (int k = 0; k < 2; ++k) dst[m][k] = *(const PG8_LAS bf16x8*)(lds + PG8_SA(b, h) + aoff + m * 2048 + k * 1024); } while (0)
; #define PG8_LDB(dst, b, h) do { _Pragma("unroll") for (int n = 0; n < 2; ++n) _Pragma("unroll") for (int k = 0; k < 2; ++k) dst[n][k] = *(const PG8_LAS bf16x8*)(lds + PG8_SB(b, h) + boff + n * 2048 + k * 1024); } while (0)
; #define PG8_MMA(ai, bj, At, Bt) do { __builtin_amdgcn_s_setprio(1); _Pragma("unroll") for (int m = 0; m < 4; ++m) _Pragma("unroll") for (int n = 0; n < 2; ++n) _Pragma("unroll") for (int k = 0; k < 2; ++k) \
;         acc[ai][bj][m][n] = __builtin_amdgcn_mfma_f32_16x16x32_bf16(Bt[n][k], At[m][k], acc[ai][bj][m][n], 0, 0, 0); __builtin_amdgcn_s_setprio(0); } while (0)
; #define PG8_WAIT_V(n) asm volatile("s_waitcnt vmcnt(" #n ")" ::: "memory")
; #define PG8_WAIT_L(n) asm volatile("s_waitcnt lgkmcnt(" #n ")" ::: "memory")
; #define PG8_BAR __builtin_amdgcn_s_barrier()
; #define PG8_SCHED __builtin_amdgcn_sched_barrier(0)
; template <class Epi, class Sched, bool ALIGN_EPI = false, bool SP2 = false>
; __device__ __forceinline__ void gemm_phase(PG8_LAS unsigned char* lds, const Gemm g, const Sched& S, const Epi& E) {
;     ...
;             PG8_WAIT_V(8); PG8_WAIT_L(0); PG8_BAR; PG8_MMA(1, 0, At, B0); PG8_MMA(1, 1, At, B1); PG8_BAR; PG8_SCHED;
;             PG8_LDB(B0, 1, 0); PG8_LDB(B1, 1, 1); PG8_SCHED; PG8_LDA(At, 1, 0); PG8_STAGE(PG8_SA(0, 1), a2 + hstep, voffA);
;             PG8_WAIT_V(8); PG8_WAIT_L(0); PG8_BAR; PG8_MMA(0, 0, At, B0); PG8_MMA(0, 1, At, B1); PG8_BAR; PG8_SCHED;
	v_mfma_f32_16x16x32_bf16 v[60:63], v[144:147], v[188:191], v[60:63]
	v_mfma_f32_16x16x32_bf16 v[60:63], v[160:163], v[192:195], v[60:63]
	v_mfma_f32_16x16x32_bf16 v[44:47], v[144:147], v[196:199], v[44:47]
	v_mfma_f32_16x16x32_bf16 v[44:47], v[160:163], v[200:203], v[44:47]
	v_mfma_f32_16x16x32_bf16 v[28:31], v[144:147], v[204:207], v[28:31]
	v_mfma_f32_16x16x32_bf16 v[28:31], v[160:163], v[208:211], v[28:31]
	v_mfma_f32_16x16x32_bf16 v[12:15], v[144:147], v[212:215], v[12:15]
	v_mfma_f32_16x16x32_bf16 v[12:15], v[160:163], v[216:219], v[12:15]
	v_mfma_f32_16x16x32_bf16 v[8:11], v[164:167], v[212:215], v[8:11]
	v_mfma_f32_16x16x32_bf16 v[8:11], v[168:171], v[216:219], v[8:11]
	v_mfma_f32_16x16x32_bf16 v[24:27], v[164:167], v[204:207], v[24:27]
	v_mfma_f32_16x16x32_bf16 v[24:27], v[168:171], v[208:211], v[24:27]
	v_mfma_f32_16x16x32_bf16 v[40:43], v[164:167], v[196:199], v[40:43]
	v_mfma_f32_16x16x32_bf16 v[40:43], v[168:171], v[200:203], v[40:43]
	v_mfma_f32_16x16x32_bf16 v[56:59], v[164:167], v[188:191], v[56:59]
	v_mfma_f32_16x16x32_bf16 v[56:59], v[168:171], v[192:195], v[56:59]
	v_mfma_f32_16x16x32_bf16 v[52:55], v[172:175], v[188:191], v[52:55]
	v_mfma_f32_16x16x32_bf16 v[52:55], v[176:179], v[192:195], v[52:55]
	v_mfma_f32_16x16x32_bf16 v[36:39], v[172:175], v[196:199], v[36:39]
	v_mfma_f32_16x16x32_bf16 v[36:39], v[176:179], v[200:203], v[36:39]
	v_mfma_f32_16x16x32_bf16 v[20:23], v[172:175], v[204:207], v[20:23]
	v_mfma_f32_16x16x32_bf16 v[20:23], v[176:179], v[208:211], v[20:23]
	v_mfma_f32_16x16x32_bf16 v[4:7], v[172:175], v[212:215], v[4:7]
	v_mfma_f32_16x16x32_bf16 v[4:7], v[176:179], v[216:219], v[4:7]
	v_mfma_f32_16x16x32_bf16 v[0:3], v[180:183], v[212:215], v[0:3]
	v_mfma_f32_16x16x32_bf16 v[0:3], v[184:187], v[216:219], v[0:3]
	v_mfma_f32_16x16x32_bf16 v[16:19], v[180:183], v[204:207], v[16:19]
	v_mfma_f32_16x16x32_bf16 v[16:19], v[184:187], v[208:211], v[16:19]
	s_setprio 2
	s_barrier
	v_mfma_f32_16x16x32_bf16 v[32:35], v[180:183], v[196:199], v[32:35]
	v_mfma_f32_16x16x32_bf16 v[32:35], v[184:187], v[200:203], v[32:35]
	v_mfma_f32_16x16x32_bf16 v[48:51], v[180:183], v[188:191], v[48:51]
	v_mfma_f32_16x16x32_bf16 v[48:51], v[184:187], v[192:195], v[48:51]
	s_setprio 0
	s_add_i32 s59, 0, 0x18000
	v_add_u32_e32 v159, s59, v153
	s_add_i32 s61, 0, 0x1c000
	ds_read_b128 v[144:147], v159
	ds_read_b128 v[160:163], v159 offset:1024
	ds_read_b128 v[164:167], v159 offset:2048
	ds_read_b128 v[168:171], v159 offset:3072
	v_add_u32_e32 v159, s61, v153
	ds_read_b128 v[172:175], v159
	ds_read_b128 v[176:179], v159 offset:1024
	ds_read_b128 v[180:183], v159 offset:2048
	ds_read_b128 v[184:187], v159 offset:3072
	s_add_u32 s42, s42, 0x160000
	s_addc_u32 s43, s43, 0
	s_mov_b32 m0, s44
	v_lshl_add_u64 v[228:229], s[42:43], 0, v[128:129]
	ds_read_b128 v[188:191], v157 offset:32768
	ds_read_b128 v[192:195], v157 offset:33792
	ds_read_b128 v[196:199], v157 offset:34816
	ds_read_b128 v[200:203], v157 offset:35840
	ds_read_b128 v[204:207], v157 offset:36864
	ds_read_b128 v[208:211], v157 offset:37888
	ds_read_b128 v[212:215], v157 offset:38912
	ds_read_b128 v[216:219], v157 offset:39936
	global_load_lds_dwordx4 v[228:229], off
	v_lshl_add_u64 v[228:229], s[42:43], 0, v[132:133]
	s_mov_b32 m0, s45
	s_nop 0
	global_load_lds_dwordx4 v[228:229], off
	s_waitcnt vmcnt(8)
	s_waitcnt lgkmcnt(0)
	s_setprio 1
	s_barrier
	v_mfma_f32_16x16x32_bf16 v[124:127], v[144:147], v[188:191], v[124:127]
	v_mfma_f32_16x16x32_bf16 v[124:127], v[160:163], v[192:195], v[124:127]
	v_mfma_f32_16x16x32_bf16 v[108:111], v[144:147], v[196:199], v[108:111]
	v_mfma_f32_16x16x32_bf16 v[108:111], v[160:163], v[200:203], v[108:111]
	v_mfma_f32_16x16x32_bf16 v[92:95], v[144:147], v[204:207], v[92:95]
	v_mfma_f32_16x16x32_bf16 v[92:95], v[160:163], v[208:211], v[92:95]
	v_mfma_f32_16x16x32_bf16 v[76:79], v[144:147], v[212:215], v[76:79]
	v_mfma_f32_16x16x32_bf16 v[76:79], v[160:163], v[216:219], v[76:79]
	v_mfma_f32_16x16x32_bf16 v[72:75], v[164:167], v[212:215], v[72:75]
	v_mfma_f32_16x16x32_bf16 v[72:75], v[168:171], v[216:219], v[72:75]
	v_mfma_f32_16x16x32_bf16 v[88:91], v[164:167], v[204:207], v[88:91]
	v_mfma_f32_16x16x32_bf16 v[88:91], v[168:171], v[208:211], v[88:91]
	v_mfma_f32_16x16x32_bf16 v[104:107], v[164:167], v[196:199], v[104:107]
	v_mfma_f32_16x16x32_bf16 v[104:107], v[168:171], v[200:203], v[104:107]
	v_mfma_f32_16x16x32_bf16 v[120:123], v[164:167], v[188:191], v[120:123]
	v_mfma_f32_16x16x32_bf16 v[120:123], v[168:171], v[192:195], v[120:123]
	v_mfma_f32_16x16x32_bf16 v[116:119], v[172:175], v[188:191], v[116:119]
	v_mfma_f32_16x16x32_bf16 v[116:119], v[176:179], v[192:195], v[116:119]
	v_mfma_f32_16x16x32_bf16 v[100:103], v[172:175], v[196:199], v[100:103]
	v_mfma_f32_16x16x32_bf16 v[100:103], v[176:179], v[200:203], v[100:103]
	v_mfma_f32_16x16x32_bf16 v[84:87], v[172:175], v[204:207], v[84:87]
	v_mfma_f32_16x16x32_bf16 v[84:87], v[176:179], v[208:211], v[84:87]
	v_mfma_f32_16x16x32_bf16 v[68:71], v[172:175], v[212:215], v[68:71]
	v_mfma_f32_16x16x32_bf16 v[68:71], v[176:179], v[216:219], v[68:71]
	v_mfma_f32_16x16x32_bf16 v[64:67], v[180:183], v[212:215], v[64:67]
	v_mfma_f32_16x16x32_bf16 v[64:67], v[184:187], v[216:219], v[64:67]
	v_mfma_f32_16x16x32_bf16 v[80:83], v[180:183], v[204:207], v[80:83]
	v_mfma_f32_16x16x32_bf16 v[80:83], v[184:187], v[208:211], v[80:83]
	s_setprio 2
	s_barrier
; #define PG8_STAGE(bufoff, gbase, voff) do { _Pragma("unroll") for (int _i = 0; _i < 2; ++_i) \
;         __builtin_amdgcn_global_load_lds((const unsigned*)((const char*)(gbase) + (voff)[_i]), (PG8_LAS unsigned*)(lds + (bufoff) + ldsw + _i * 8192), 16, 0, 0); } while (0)
; #define PG8_LDA(dst, b, h) do { _Pragma("unroll") for (int m = 0; m < 4; ++m) _Pragma("unroll") for (int k = 0; k < 2; ++k) dst[m][k] = *(const PG8_LAS bf16x8*)(lds + PG8_SA(b, h) + aoff + m * 2048 + k * 1024); } while (0)
; #define PG8_MMA(ai, bj, At, Bt) do { __builtin_amdgcn_s_setprio(1); _Pragma("unroll") for (int m = 0; m < 4; ++m) _Pragma("unroll") for (int n = 0; n < 2; ++n) _Pragma("unroll") for (int k = 0; k < 2; ++k) \
;         acc[ai][bj][m][n] = __builtin_amdgcn_mfma_f32_16x16x32_bf16(Bt[n][k], At[m][k], acc[ai][bj][m][n], 0, 0, 0); __builtin_amdgcn_s_setprio(0); } while (0)
; #define PG8_WAIT_V(n) asm volatile("s_waitcnt vmcnt(" #n ")" ::: "memory")
; #define PG8_WAIT_L(n) asm volatile("s_waitcnt lgkmcnt(" #n ")" ::: "memory")
; #define PG8_BAR __builtin_amdgcn_s_barrier()
; #define PG8_SCHED __builtin_amdgcn_sched_barrier(0)
; template <class Epi, class Sched, bool ALIGN_EPI = false, bool SP2 = false>
; __device__ __forceinline__ void gemm_phase(PG8_LAS unsigned char* lds, const Gemm g, const Sched& S, const Epi& E) {
;     ...
;         for (int t = 0; t < nt; t += 2) {
;     ...
;             PG8_WAIT_V(8); PG8_WAIT_L(0); PG8_BAR; PG8_MMA(0, 0, At, B0); PG8_MMA(0, 1, At, B1); PG8_BAR; PG8_SCHED;
;             PG8_LDA(At, 1, 1); PG8_STAGE(PG8_SB(1, 0), b3, voffB); PG8_STAGE(PG8_SB(1, 1), b3 + hstep, voffB); PG8_STAGE(PG8_SA(1, 0), a3, voffA);
;             PG8_WAIT_V(8); PG8_WAIT_L(0); PG8_BAR; PG8_MMA(1, 0, At, B0); PG8_MMA(1, 1, At, B1); PG8_BAR; PG8_SCHED;
	v_mfma_f32_16x16x32_bf16 v[96:99], v[180:183], v[196:199], v[96:99]
	v_mfma_f32_16x16x32_bf16 v[96:99], v[184:187], v[200:203], v[96:99]
	v_mfma_f32_16x16x32_bf16 v[112:115], v[180:183], v[188:191], v[112:115]
	v_mfma_f32_16x16x32_bf16 v[112:115], v[184:187], v[192:195], v[112:115]
	s_setprio 0
	s_add_i32 s42, s59, s3
	v_lshl_add_u64 v[220:221], v[220:221], 0, s[16:17]
	s_mov_b32 m0, s42
	ds_read_b128 v[188:191], v157 offset:49152
	ds_read_b128 v[192:195], v157 offset:50176
	ds_read_b128 v[196:199], v157 offset:51200
	ds_read_b128 v[200:203], v157 offset:52224
	ds_read_b128 v[204:207], v157 offset:53248
	ds_read_b128 v[208:211], v157 offset:54272
	ds_read_b128 v[212:215], v157 offset:55296
	ds_read_b128 v[216:219], v157 offset:56320
	global_load_lds_dwordx4 v[220:221], off
	s_add_i32 m0, s42, 0x2000
	s_add_u32 s40, s40, 0x160080
	v_lshl_add_u64 v[220:221], v[222:223], 0, s[16:17]
	s_addc_u32 s41, s41, 0
	s_add_i32 s42, s61, s3
	global_load_lds_dwordx4 v[220:221], off
	v_lshl_add_u64 v[220:221], s[40:41], 0, v[130:131]
	s_mov_b32 m0, s42
	s_nop 0
	global_load_lds_dwordx4 v[220:221], off
	v_lshl_add_u64 v[220:221], s[40:41], 0, v[134:135]
	s_add_i32 m0, s42, 0x2000
	s_nop 0
	global_load_lds_dwordx4 v[220:221], off
	v_lshl_add_u64 v[220:221], v[224:225], 0, s[16:17]
	s_mov_b32 m0, s49
	s_nop 0
	global_load_lds_dwordx4 v[220:221], off
	v_lshl_add_u64 v[220:221], v[226:227], 0, s[16:17]
	s_mov_b32 m0, s50
	s_nop 0
	global_load_lds_dwordx4 v[220:221], off
	s_waitcnt vmcnt(8)
	s_waitcnt lgkmcnt(0)
	s_setprio 1
	s_barrier
	v_mfma_f32_16x16x32_bf16 v[60:63], v[144:147], v[188:191], v[60:63]
	v_mfma_f32_16x16x32_bf16 v[60:63], v[160:163], v[192:195], v[60:63]
	v_mfma_f32_16x16x32_bf16 v[44:47], v[144:147], v[196:199], v[44:47]
	v_mfma_f32_16x16x32_bf16 v[44:47], v[160:163], v[200:203], v[44:47]
	v_mfma_f32_16x16x32_bf16 v[28:31], v[144:147], v[204:207], v[28:31]
	v_mfma_f32_16x16x32_bf16 v[28:31], v[160:163], v[208:211], v[28:31]
	v_mfma_f32_16x16x32_bf16 v[12:15], v[144:147], v[212:215], v[12:15]
	v_mfma_f32_16x16x32_bf16 v[12:15], v[160:163], v[216:219], v[12:15]
	v_mfma_f32_16x16x32_bf16 v[8:11], v[164:167], v[212:215], v[8:11]
	v_mfma_f32_16x16x32_bf16 v[8:11], v[168:171], v[216:219], v[8:11]
	v_mfma_f32_16x16x32_bf16 v[24:27], v[164:167], v[204:207], v[24:27]
	v_mfma_f32_16x16x32_bf16 v[24:27], v[168:171], v[208:211], v[24:27]
	v_mfma_f32_16x16x32_bf16 v[40:43], v[164:167], v[196:199], v[40:43]
	v_mfma_f32_16x16x32_bf16 v[40:43], v[168:171], v[200:203], v[40:43]
	v_mfma_f32_16x16x32_bf16 v[56:59], v[164:167], v[188:191], v[56:59]
	v_mfma_f32_16x16x32_bf16 v[56:59], v[168:171], v[192:195], v[56:59]
	v_mfma_f32_16x16x32_bf16 v[52:55], v[172:175], v[188:191], v[52:55]
	v_mfma_f32_16x16x32_bf16 v[52:55], v[176:179], v[192:195], v[52:55]
	v_mfma_f32_16x16x32_bf16 v[36:39], v[172:175], v[196:199], v[36:39]
	v_mfma_f32_16x16x32_bf16 v[36:39], v[176:179], v[200:203], v[36:39]
	v_mfma_f32_16x16x32_bf16 v[20:23], v[172:175], v[204:207], v[20:23]
	v_mfma_f32_16x16x32_bf16 v[20:23], v[176:179], v[208:211], v[20:23]
	v_mfma_f32_16x16x32_bf16 v[4:7], v[172:175], v[212:215], v[4:7]
	v_mfma_f32_16x16x32_bf16 v[4:7], v[176:179], v[216:219], v[4:7]
	v_mfma_f32_16x16x32_bf16 v[0:3], v[180:183], v[212:215], v[0:3]
	v_mfma_f32_16x16x32_bf16 v[0:3], v[184:187], v[216:219], v[0:3]
	v_mfma_f32_16x16x32_bf16 v[16:19], v[180:183], v[204:207], v[16:19]
	v_mfma_f32_16x16x32_bf16 v[16:19], v[184:187], v[208:211], v[16:19]
	s_setprio 2
	s_barrier
	v_mfma_f32_16x16x32_bf16 v[32:35], v[180:183], v[196:199], v[32:35]
	v_mfma_f32_16x16x32_bf16 v[32:35], v[184:187], v[200:203], v[32:35]
	v_mfma_f32_16x16x32_bf16 v[48:51], v[180:183], v[188:191], v[48:51]
	v_mfma_f32_16x16x32_bf16 v[48:51], v[184:187], v[192:195], v[48:51]
	s_setprio 0
	s_add_i32 s58, s58, 2
	s_add_u32 s38, s38, 0x100
	s_addc_u32 s39, s39, 0
	s_add_u32 s11, s11, 0x100
	s_addc_u32 s57, s57, 0
	s_cmpk_gt_u32 s58, 0x55
	s_cbranch_scc0 .LBB0_779
	s_and_b64 vcc, exec, s[20:21]
	s_cbranch_vccz .LBB0_782
	s_barrier
